# B-fragment reads of the 12-read loader segments moved one segment earlier into the read-free segments (balance 12/4/8/0 -> 8/4/8/4)
# baseline (speedup 1.0000x reference)
;     __device__ __forceinline__ void prep(int pm, int par, LAS unsigned char* lds) const { if (fold) prep_rowstats(stat, pm, par, lds); }
;     __device__ __forceinline__ void prep(int pm, int par, LAS unsigned char* lds) const { if (!ident) prep_rowstats(stat, pm, par, lds); }
;     __device__ __forceinline__ void prep(int pm, int par, LAS unsigned char* lds) const { prep_rowstats(stat, pm, par, lds); }
; #define G_STAGE(bufoff, gbase) do { _Pragma("unroll") for (int _i = 0; _i < 2; ++_i) \
;         __builtin_amdgcn_global_load_lds((const unsigned*)((const char*)(gbase) + voff[_i]), (LAS unsigned*)(lds + (bufoff) + ldsw + _i * 8192), 16, 0, 0); } while (0)
; #define G_LDA(dst, b, h) do { _Pragma("unroll") for (int m = 0; m < 4; ++m) _Pragma("unroll") for (int k = 0; k < 2; ++k) dst[m][k] = *(const LAS bf16x8*)(lds + G_SA(b, h) + aoff + m * 2048 + k * 1024); } while (0)
; #define G_LDB(dst, b, h) do { _Pragma("unroll") for (int n = 0; n < 2; ++n) _Pragma("unroll") for (int k = 0; k < 2; ++k) dst[n][k] = *(const LAS bf16x8*)(lds + G_SB(b, h) + boff + n * 2048 + k * 1024); } while (0)
; #define G_WAIT_V(n) asm volatile("s_waitcnt vmcnt(" #n ")" ::: "memory")
; #define G_WAIT_L(n) asm volatile("s_waitcnt lgkmcnt(" #n ")" ::: "memory")
; #define G_BAR __builtin_amdgcn_s_barrier()
; template <class Epi>
; __device__ __forceinline__ void gemm_phase(LAS unsigned char* lds, const bf16_t* Ag, const bf16_t* Btg, const int K, const int nM, const int nN, const Epi& E) {
;     ...
;             const char* a1 = cA + (size_t)(t + 1) * kstep;
;             const char* a2 = last ? nA : cA + (size_t)(t + 2) * kstep; const char* b2 = last ? nB : cB + (size_t)(t + 2) * kstep;
;             const char* a3 = a2 + kstep; const char* b3 = b2 + kstep;
;             if (last && has_next && pmn != pm) E.prep(pmn, par ^ 1, lds);
;             G_LDB(B0, 0, 0); G_SCHED; G_LDA(At, 0, 0); G_STAGE(G_SA(1, 1), a1 + hstep);
;             G_WAIT_L(8); G_BAR; G_WAIT_L(0); G_MMA(0, 0, At, B0); G_BAR; G_SCHED;
;             G_LDB(B1, 0, 1); G_STAGE(G_SB(0, 0), b2);
;             G_BAR; G_WAIT_L(0); G_MMA(0, 1, At, B1); G_BAR;
;             G_LDA(At, 0, 1); G_STAGE(G_SA(0, 0), a2);
;             G_BAR; G_WAIT_L(0); G_MMA(1, 0, At, B0); G_BAR; G_SCHED;
;             G_STAGE(G_SB(0, 1), b2 + hstep);
;             G_WAIT_V(6); G_BAR; G_MMA(1, 1, At, B1); G_BAR;
.LBB0_78:
	s_add_u32 s12, s50, 0xfffc0080
	s_addc_u32 s26, s51, -1
	s_and_b64 s[52:53], s[52:53], exec
	s_cselect_b32 s55, s26, s43
	s_cselect_b32 s54, s12, s42
	s_cselect_b32 s53, s72, s15
	s_cselect_b32 s52, s71, s69
	ds_read_b128 v[124:127], v217
	ds_read_b128 v[128:131], v217 offset:1024
	ds_read_b128 v[132:135], v217 offset:2048
	ds_read_b128 v[136:139], v217 offset:3072
.LmainW_78:
	s_add_i32 m0, s58, 0xc000
	ds_read_b128 v[140:143], v186
	ds_read_b128 v[148:151], v186 offset:1024
	ds_read_b128 v[152:155], v186 offset:2048
	ds_read_b128 v[156:159], v186 offset:3072
	ds_read_b128 v[188:191], v186 offset:4096
	ds_read_b128 v[192:195], v186 offset:5120
	ds_read_b128 v[222:225], v186 offset:6144
	global_load_lds_dwordx4 v170, s[50:51]
	s_add_i32 m0, s58, 0xe000
	ds_read_b128 v[226:229], v186 offset:7168
	global_load_lds_dwordx4 v168, s[50:51]
	s_waitcnt lgkmcnt(8)
	s_barrier
	s_waitcnt lgkmcnt(0)
	s_waitcnt lgkmcnt(0)
	v_mfma_f32_16x16x32_bf16 v[164:167], v[124:127], v[140:143], v[164:167]
	v_mfma_f32_16x16x32_bf16 v[160:163], v[132:135], v[140:143], v[160:163]
	v_mfma_f32_16x16x32_bf16 v[116:119], v[124:127], v[152:155], v[116:119]
	v_mfma_f32_16x16x32_bf16 v[112:115], v[132:135], v[152:155], v[112:115]
	v_mfma_f32_16x16x32_bf16 v[100:103], v[124:127], v[188:191], v[100:103]
	v_mfma_f32_16x16x32_bf16 v[96:99], v[132:135], v[188:191], v[96:99]
	v_mfma_f32_16x16x32_bf16 v[84:87], v[124:127], v[222:225], v[84:87]
	v_mfma_f32_16x16x32_bf16 v[80:83], v[132:135], v[222:225], v[80:83]
	v_mfma_f32_16x16x32_bf16 v[164:167], v[128:131], v[148:151], v[164:167]
	v_mfma_f32_16x16x32_bf16 v[160:163], v[136:139], v[148:151], v[160:163]
	v_mfma_f32_16x16x32_bf16 v[116:119], v[128:131], v[156:159], v[116:119]
	v_mfma_f32_16x16x32_bf16 v[112:115], v[136:139], v[156:159], v[112:115]
	v_mfma_f32_16x16x32_bf16 v[100:103], v[128:131], v[192:195], v[100:103]
	v_mfma_f32_16x16x32_bf16 v[96:99], v[136:139], v[192:195], v[96:99]
	v_mfma_f32_16x16x32_bf16 v[84:87], v[128:131], v[226:229], v[84:87]
	v_mfma_f32_16x16x32_bf16 v[80:83], v[136:139], v[226:229], v[80:83]
	s_barrier
	ds_read_b128 v[230:233], v217 offset:16384
	ds_read_b128 v[234:237], v217 offset:17408
	s_add_i32 m0, s57, 0x10000
	ds_read_b128 v[238:241], v217 offset:18432
	global_load_lds_dwordx4 v0, s[52:53]
	s_add_i32 m0, s57, 0x12000
	ds_read_b128 v[242:245], v217 offset:19456
	global_load_lds_dwordx4 v2, s[52:53]
	s_barrier
	s_waitcnt lgkmcnt(0)
	s_waitcnt lgkmcnt(0)
	v_mfma_f32_16x16x32_bf16 v[144:147], v[230:233], v[140:143], v[144:147]
	v_mfma_f32_16x16x32_bf16 v[120:123], v[238:241], v[140:143], v[120:123]
	v_mfma_f32_16x16x32_bf16 v[108:111], v[230:233], v[152:155], v[108:111]
	v_mfma_f32_16x16x32_bf16 v[104:107], v[238:241], v[152:155], v[104:107]
	v_mfma_f32_16x16x32_bf16 v[92:95], v[230:233], v[188:191], v[92:95]
	v_mfma_f32_16x16x32_bf16 v[88:91], v[238:241], v[188:191], v[88:91]
	v_mfma_f32_16x16x32_bf16 v[76:79], v[230:233], v[222:225], v[76:79]
	v_mfma_f32_16x16x32_bf16 v[72:75], v[238:241], v[222:225], v[72:75]
	v_mfma_f32_16x16x32_bf16 v[144:147], v[234:237], v[148:151], v[144:147]
	v_mfma_f32_16x16x32_bf16 v[120:123], v[242:245], v[148:151], v[120:123]
	v_mfma_f32_16x16x32_bf16 v[108:111], v[234:237], v[156:159], v[108:111]
	v_mfma_f32_16x16x32_bf16 v[104:107], v[242:245], v[156:159], v[104:107]
	v_mfma_f32_16x16x32_bf16 v[92:95], v[234:237], v[192:195], v[92:95]
	v_mfma_f32_16x16x32_bf16 v[88:91], v[242:245], v[192:195], v[88:91]
	v_mfma_f32_16x16x32_bf16 v[76:79], v[234:237], v[226:229], v[76:79]
	v_mfma_f32_16x16x32_bf16 v[72:75], v[242:245], v[226:229], v[72:75]
	s_mov_b32 m0, s58
	s_barrier
	ds_read_b128 v[140:143], v186 offset:16384
	ds_read_b128 v[148:151], v186 offset:17408
	ds_read_b128 v[152:155], v186 offset:18432
	ds_read_b128 v[156:159], v186 offset:19456
	ds_read_b128 v[188:191], v186 offset:20480
	ds_read_b128 v[192:195], v186 offset:21504
	ds_read_b128 v[222:225], v186 offset:22528
	global_load_lds_dwordx4 v0, s[54:55]
	s_mov_b32 m0, s59
	ds_read_b128 v[226:229], v186 offset:23552
	global_load_lds_dwordx4 v2, s[54:55]
	s_waitcnt vmcnt(10)
	s_barrier
	s_waitcnt lgkmcnt(0)
	s_waitcnt lgkmcnt(0)
	v_mfma_f32_16x16x32_bf16 v[60:63], v[124:127], v[140:143], v[60:63]
	v_mfma_f32_16x16x32_bf16 v[56:59], v[132:135], v[140:143], v[56:59]
	v_mfma_f32_16x16x32_bf16 v[44:47], v[124:127], v[152:155], v[44:47]
	v_mfma_f32_16x16x32_bf16 v[40:43], v[132:135], v[152:155], v[40:43]
	v_mfma_f32_16x16x32_bf16 v[28:31], v[124:127], v[188:191], v[28:31]
	v_mfma_f32_16x16x32_bf16 v[24:27], v[132:135], v[188:191], v[24:27]
	v_mfma_f32_16x16x32_bf16 v[12:15], v[124:127], v[222:225], v[12:15]
	v_mfma_f32_16x16x32_bf16 v[8:11], v[132:135], v[222:225], v[8:11]
	v_mfma_f32_16x16x32_bf16 v[60:63], v[128:131], v[148:151], v[60:63]
	v_mfma_f32_16x16x32_bf16 v[56:59], v[136:139], v[148:151], v[56:59]
	v_mfma_f32_16x16x32_bf16 v[44:47], v[128:131], v[156:159], v[44:47]
	v_mfma_f32_16x16x32_bf16 v[40:43], v[136:139], v[156:159], v[40:43]
	v_mfma_f32_16x16x32_bf16 v[28:31], v[128:131], v[192:195], v[28:31]
	v_mfma_f32_16x16x32_bf16 v[24:27], v[136:139], v[192:195], v[24:27]
	v_mfma_f32_16x16x32_bf16 v[12:15], v[128:131], v[226:229], v[12:15]
	v_mfma_f32_16x16x32_bf16 v[8:11], v[136:139], v[226:229], v[8:11]
	s_barrier
	ds_read_b128 v[124:127], v217 offset:32768
	ds_read_b128 v[128:131], v217 offset:33792
	ds_read_b128 v[132:135], v217 offset:34816
	ds_read_b128 v[136:139], v217 offset:35840
	s_add_i32 m0, s57, 0x14000
	s_add_u32 s74, s52, 0x40000
	s_addc_u32 s75, s53, 0
	global_load_lds_dwordx4 v0, s[74:75]
	s_add_i32 m0, s57, 0x16000
	s_add_u32 s54, s54, 0x40000
	s_addc_u32 s55, s55, 0
	global_load_lds_dwordx4 v2, s[74:75]
	s_waitcnt vmcnt(6)
	s_barrier
; #define G_STAGE(bufoff, gbase) do { _Pragma("unroll") for (int _i = 0; _i < 2; ++_i) \
;         __builtin_amdgcn_global_load_lds((const unsigned*)((const char*)(gbase) + voff[_i]), (LAS unsigned*)(lds + (bufoff) + ldsw + _i * 8192), 16, 0, 0); } while (0)
; #define G_LDA(dst, b, h) do { _Pragma("unroll") for (int m = 0; m < 4; ++m) _Pragma("unroll") for (int k = 0; k < 2; ++k) dst[m][k] = *(const LAS bf16x8*)(lds + G_SA(b, h) + aoff + m * 2048 + k * 1024); } while (0)
; #define G_LDB(dst, b, h) do { _Pragma("unroll") for (int n = 0; n < 2; ++n) _Pragma("unroll") for (int k = 0; k < 2; ++k) dst[n][k] = *(const LAS bf16x8*)(lds + G_SB(b, h) + boff + n * 2048 + k * 1024); } while (0)
; #define G_MMA(ai, bj, At, Bt) do { __builtin_amdgcn_s_setprio(1); _Pragma("unroll") for (int m = 0; m < 4; ++m) _Pragma("unroll") for (int n = 0; n < 2; ++n) _Pragma("unroll") for (int k = 0; k < 2; ++k) \
;         acc[ai][bj][m][n] = MFMA16(Bt[n][k], At[m][k], acc[ai][bj][m][n]); __builtin_amdgcn_s_setprio(0); } while (0)
; #define G_WAIT_V(n) asm volatile("s_waitcnt vmcnt(" #n ")" ::: "memory")
; #define G_WAIT_L(n) asm volatile("s_waitcnt lgkmcnt(" #n ")" ::: "memory")
; #define G_BAR __builtin_amdgcn_s_barrier()
; #define G_SCHED __builtin_amdgcn_sched_barrier(0)
; template <class Epi>
; __device__ __forceinline__ void gemm_phase(LAS unsigned char* lds, const bf16_t* Ag, const bf16_t* Btg, const int K, const int nM, const int nN, const Epi& E) {
;     ...
;             const char* a1 = cA + (size_t)(t + 1) * kstep;
;             const char* a2 = last ? nA : cA + (size_t)(t + 2) * kstep; const char* b2 = last ? nB : cB + (size_t)(t + 2) * kstep;
;             const char* a3 = a2 + kstep; const char* b3 = b2 + kstep;
;     ...
;             G_WAIT_V(6); G_BAR; G_MMA(1, 1, At, B1); G_BAR;
;             G_LDB(B0, 1, 0); G_SCHED; G_LDA(At, 1, 0); G_STAGE(G_SA(0, 1), a2 + hstep);
;             G_WAIT_L(8); G_BAR; G_WAIT_L(0); G_MMA(0, 0, At, B0); G_BAR; G_SCHED;
;             G_LDB(B1, 1, 1); G_STAGE(G_SB(1, 0), b3);
;             G_BAR; G_WAIT_L(0); G_MMA(0, 1, At, B1); G_BAR;
;             G_LDA(At, 1, 1); G_STAGE(G_SA(1, 0), a3);
;             G_BAR; G_WAIT_L(0); G_MMA(1, 0, At, B0); G_BAR; G_SCHED;
;             G_STAGE(G_SB(1, 1), b3 + hstep);
;             G_WAIT_V(6); G_BAR; G_MMA(1, 1, At, B1); G_BAR;
	v_mfma_f32_16x16x32_bf16 v[68:71], v[230:233], v[140:143], v[68:71]
	v_mfma_f32_16x16x32_bf16 v[64:67], v[238:241], v[140:143], v[64:67]
	v_mfma_f32_16x16x32_bf16 v[52:55], v[230:233], v[152:155], v[52:55]
	v_mfma_f32_16x16x32_bf16 v[48:51], v[238:241], v[152:155], v[48:51]
	v_mfma_f32_16x16x32_bf16 v[36:39], v[230:233], v[188:191], v[36:39]
	v_mfma_f32_16x16x32_bf16 v[32:35], v[238:241], v[188:191], v[32:35]
	v_mfma_f32_16x16x32_bf16 v[20:23], v[230:233], v[222:225], v[20:23]
	v_mfma_f32_16x16x32_bf16 v[16:19], v[238:241], v[222:225], v[16:19]
	v_mfma_f32_16x16x32_bf16 v[68:71], v[234:237], v[148:151], v[68:71]
	v_mfma_f32_16x16x32_bf16 v[64:67], v[242:245], v[148:151], v[64:67]
	v_mfma_f32_16x16x32_bf16 v[52:55], v[234:237], v[156:159], v[52:55]
	v_mfma_f32_16x16x32_bf16 v[48:51], v[242:245], v[156:159], v[48:51]
	v_mfma_f32_16x16x32_bf16 v[36:39], v[234:237], v[192:195], v[36:39]
	v_mfma_f32_16x16x32_bf16 v[32:35], v[242:245], v[192:195], v[32:35]
	v_mfma_f32_16x16x32_bf16 v[20:23], v[234:237], v[226:229], v[20:23]
	v_mfma_f32_16x16x32_bf16 v[16:19], v[242:245], v[226:229], v[16:19]
	s_barrier
	s_mov_b32 m0, s60
	ds_read_b128 v[140:143], v186 offset:32768
	ds_read_b128 v[148:151], v186 offset:33792
	ds_read_b128 v[152:155], v186 offset:34816
	ds_read_b128 v[156:159], v186 offset:35840
	ds_read_b128 v[188:191], v186 offset:36864
	ds_read_b128 v[192:195], v186 offset:37888
	ds_read_b128 v[222:225], v186 offset:38912
	global_load_lds_dwordx4 v0, s[54:55]
	s_mov_b32 m0, s61
	ds_read_b128 v[226:229], v186 offset:39936
	global_load_lds_dwordx4 v2, s[54:55]
	s_waitcnt lgkmcnt(8)
	s_barrier
	s_waitcnt lgkmcnt(0)
	s_waitcnt lgkmcnt(0)
	v_mfma_f32_16x16x32_bf16 v[164:167], v[124:127], v[140:143], v[164:167]
	v_mfma_f32_16x16x32_bf16 v[160:163], v[132:135], v[140:143], v[160:163]
	v_mfma_f32_16x16x32_bf16 v[116:119], v[124:127], v[152:155], v[116:119]
	v_mfma_f32_16x16x32_bf16 v[112:115], v[132:135], v[152:155], v[112:115]
	v_mfma_f32_16x16x32_bf16 v[100:103], v[124:127], v[188:191], v[100:103]
	v_mfma_f32_16x16x32_bf16 v[96:99], v[132:135], v[188:191], v[96:99]
	v_mfma_f32_16x16x32_bf16 v[84:87], v[124:127], v[222:225], v[84:87]
	v_mfma_f32_16x16x32_bf16 v[80:83], v[132:135], v[222:225], v[80:83]
	v_mfma_f32_16x16x32_bf16 v[164:167], v[128:131], v[148:151], v[164:167]
	v_mfma_f32_16x16x32_bf16 v[160:163], v[136:139], v[148:151], v[160:163]
	v_mfma_f32_16x16x32_bf16 v[116:119], v[128:131], v[156:159], v[116:119]
	v_mfma_f32_16x16x32_bf16 v[112:115], v[136:139], v[156:159], v[112:115]
	v_mfma_f32_16x16x32_bf16 v[100:103], v[128:131], v[192:195], v[100:103]
	v_mfma_f32_16x16x32_bf16 v[96:99], v[136:139], v[192:195], v[96:99]
	v_mfma_f32_16x16x32_bf16 v[84:87], v[128:131], v[226:229], v[84:87]
	v_mfma_f32_16x16x32_bf16 v[80:83], v[136:139], v[226:229], v[80:83]
	s_barrier
	s_add_i32 m0, s57, 0x18000
	ds_read_b128 v[230:233], v217 offset:49152
	ds_read_b128 v[234:237], v217 offset:50176
	ds_read_b128 v[238:241], v217 offset:51200
	s_add_u32 s98, s52, 0x80
	s_addc_u32 s99, s53, 0
	global_load_lds_dwordx4 v0, s[98:99]
	s_add_i32 m0, s57, 0x1a000
	ds_read_b128 v[242:245], v217 offset:52224
	global_load_lds_dwordx4 v2, s[98:99]
	s_barrier
	s_waitcnt lgkmcnt(0)
	s_waitcnt lgkmcnt(0)
	v_mfma_f32_16x16x32_bf16 v[144:147], v[230:233], v[140:143], v[144:147]
	v_mfma_f32_16x16x32_bf16 v[120:123], v[238:241], v[140:143], v[120:123]
	v_mfma_f32_16x16x32_bf16 v[108:111], v[230:233], v[152:155], v[108:111]
	v_mfma_f32_16x16x32_bf16 v[104:107], v[238:241], v[152:155], v[104:107]
	v_mfma_f32_16x16x32_bf16 v[92:95], v[230:233], v[188:191], v[92:95]
	v_mfma_f32_16x16x32_bf16 v[88:91], v[238:241], v[188:191], v[88:91]
	v_mfma_f32_16x16x32_bf16 v[76:79], v[230:233], v[222:225], v[76:79]
	v_mfma_f32_16x16x32_bf16 v[72:75], v[238:241], v[222:225], v[72:75]
	v_mfma_f32_16x16x32_bf16 v[144:147], v[234:237], v[148:151], v[144:147]
	v_mfma_f32_16x16x32_bf16 v[120:123], v[242:245], v[148:151], v[120:123]
	v_mfma_f32_16x16x32_bf16 v[108:111], v[234:237], v[156:159], v[108:111]
	v_mfma_f32_16x16x32_bf16 v[104:107], v[242:245], v[156:159], v[104:107]
	v_mfma_f32_16x16x32_bf16 v[92:95], v[234:237], v[192:195], v[92:95]
	v_mfma_f32_16x16x32_bf16 v[88:91], v[242:245], v[192:195], v[88:91]
	v_mfma_f32_16x16x32_bf16 v[76:79], v[234:237], v[226:229], v[76:79]
	v_mfma_f32_16x16x32_bf16 v[72:75], v[242:245], v[226:229], v[72:75]
	s_mov_b32 m0, s62
	s_barrier
	ds_read_b128 v[140:143], v186 offset:49152
	ds_read_b128 v[148:151], v186 offset:50176
	ds_read_b128 v[152:155], v186 offset:51200
	ds_read_b128 v[156:159], v186 offset:52224
	ds_read_b128 v[188:191], v186 offset:53248
	ds_read_b128 v[192:195], v186 offset:54272
	ds_read_b128 v[222:225], v186 offset:55296
	s_add_u32 s98, s54, 0xfffc0080
	s_addc_u32 s99, s55, -1
	global_load_lds_dwordx4 v0, s[98:99]
	s_mov_b32 m0, s63
	ds_read_b128 v[226:229], v186 offset:56320
	global_load_lds_dwordx4 v2, s[98:99]
	s_waitcnt vmcnt(10)
	s_barrier
	s_waitcnt lgkmcnt(0)
	s_waitcnt lgkmcnt(0)
	v_mfma_f32_16x16x32_bf16 v[60:63], v[124:127], v[140:143], v[60:63]
	v_mfma_f32_16x16x32_bf16 v[56:59], v[132:135], v[140:143], v[56:59]
	v_mfma_f32_16x16x32_bf16 v[44:47], v[124:127], v[152:155], v[44:47]
	v_mfma_f32_16x16x32_bf16 v[40:43], v[132:135], v[152:155], v[40:43]
	v_mfma_f32_16x16x32_bf16 v[28:31], v[124:127], v[188:191], v[28:31]
	v_mfma_f32_16x16x32_bf16 v[24:27], v[132:135], v[188:191], v[24:27]
	v_mfma_f32_16x16x32_bf16 v[12:15], v[124:127], v[222:225], v[12:15]
	v_mfma_f32_16x16x32_bf16 v[8:11], v[132:135], v[222:225], v[8:11]
	v_mfma_f32_16x16x32_bf16 v[60:63], v[128:131], v[148:151], v[60:63]
	v_mfma_f32_16x16x32_bf16 v[56:59], v[136:139], v[148:151], v[56:59]
	v_mfma_f32_16x16x32_bf16 v[44:47], v[128:131], v[156:159], v[44:47]
	v_mfma_f32_16x16x32_bf16 v[40:43], v[136:139], v[156:159], v[40:43]
	v_mfma_f32_16x16x32_bf16 v[28:31], v[128:131], v[192:195], v[28:31]
	v_mfma_f32_16x16x32_bf16 v[24:27], v[136:139], v[192:195], v[24:27]
	v_mfma_f32_16x16x32_bf16 v[12:15], v[128:131], v[226:229], v[12:15]
	v_mfma_f32_16x16x32_bf16 v[8:11], v[136:139], v[226:229], v[8:11]
	s_barrier
	s_add_i32 m0, s57, 0x1c000
	s_add_u32 s52, s52, 0x40080
	s_addc_u32 s53, s53, 0
	global_load_lds_dwordx4 v0, s[52:53]
	s_add_i32 m0, s57, 0x1e000
	s_add_i32 s73, s73, 2
	global_load_lds_dwordx4 v2, s[52:53]
	s_add_u32 s71, s71, 0x100
	s_addc_u32 s72, s72, 0
	s_add_u32 s50, s50, 0x100
	s_addc_u32 s51, s51, 0
	s_cmp_gt_u32 s73, 13
	s_cbranch_scc1 .LrotX_78
	ds_read_b128 v[124:127], v217
	ds_read_b128 v[128:131], v217 offset:1024
	ds_read_b128 v[132:135], v217 offset:2048
	ds_read_b128 v[136:139], v217 offset:3072
	s_cmp_lg_u32 s73, 12
	s_cselect_b64 s[52:53], -1, 0
	s_add_u32 s12, s50, 0xfffc0080
	s_addc_u32 s26, s51, -1
	s_and_b64 s[52:53], s[52:53], exec
	s_cselect_b32 s55, s26, s43
	s_cselect_b32 s54, s12, s42
	s_cselect_b32 s53, s72, s15
	s_cselect_b32 s52, s71, s69
; #define G_STAGE(bufoff, gbase) do { _Pragma("unroll") for (int _i = 0; _i < 2; ++_i) \
;         __builtin_amdgcn_global_load_lds((const unsigned*)((const char*)(gbase) + voff[_i]), (LAS unsigned*)(lds + (bufoff) + ldsw + _i * 8192), 16, 0, 0); } while (0)
; #define G_MMA(ai, bj, At, Bt) do { __builtin_amdgcn_s_setprio(1); _Pragma("unroll") for (int m = 0; m < 4; ++m) _Pragma("unroll") for (int n = 0; n < 2; ++n) _Pragma("unroll") for (int k = 0; k < 2; ++k) \
;         acc[ai][bj][m][n] = MFMA16(Bt[n][k], At[m][k], acc[ai][bj][m][n]); __builtin_amdgcn_s_setprio(0); } while (0)
; #define G_WAIT_V(n) asm volatile("s_waitcnt vmcnt(" #n ")" ::: "memory")
; #define G_BAR __builtin_amdgcn_s_barrier()
; template <class Epi>
; __device__ __forceinline__ void gemm_phase(LAS unsigned char* lds, const bf16_t* Ag, const bf16_t* Btg, const int K, const int nM, const int nN, const Epi& E) {
;     ...
;             G_STAGE(G_SB(1, 1), b3 + hstep);
;             G_WAIT_V(6); G_BAR; G_MMA(1, 1, At, B1); G_BAR;
;         }
.LrotX_78:
	s_waitcnt vmcnt(6)
	s_barrier
	v_mfma_f32_16x16x32_bf16 v[68:71], v[230:233], v[140:143], v[68:71]
	v_mfma_f32_16x16x32_bf16 v[64:67], v[238:241], v[140:143], v[64:67]
	v_mfma_f32_16x16x32_bf16 v[52:55], v[230:233], v[152:155], v[52:55]
	v_mfma_f32_16x16x32_bf16 v[48:51], v[238:241], v[152:155], v[48:51]
	v_mfma_f32_16x16x32_bf16 v[36:39], v[230:233], v[188:191], v[36:39]
	v_mfma_f32_16x16x32_bf16 v[32:35], v[238:241], v[188:191], v[32:35]
	v_mfma_f32_16x16x32_bf16 v[20:23], v[230:233], v[222:225], v[20:23]
	v_mfma_f32_16x16x32_bf16 v[16:19], v[238:241], v[222:225], v[16:19]
	v_mfma_f32_16x16x32_bf16 v[68:71], v[234:237], v[148:151], v[68:71]
	v_mfma_f32_16x16x32_bf16 v[64:67], v[242:245], v[148:151], v[64:67]
	v_mfma_f32_16x16x32_bf16 v[52:55], v[234:237], v[156:159], v[52:55]
	v_mfma_f32_16x16x32_bf16 v[48:51], v[242:245], v[156:159], v[48:51]
	v_mfma_f32_16x16x32_bf16 v[36:39], v[234:237], v[192:195], v[36:39]
	v_mfma_f32_16x16x32_bf16 v[32:35], v[242:245], v[192:195], v[32:35]
	v_mfma_f32_16x16x32_bf16 v[20:23], v[234:237], v[226:229], v[20:23]
	v_mfma_f32_16x16x32_bf16 v[16:19], v[242:245], v[226:229], v[16:19]
	s_cmp_gt_u32 s73, 13
	s_barrier
	s_cbranch_scc1 .LBB0_82
	s_cmp_lg_u32 s73, 12
	s_cbranch_scc1 .LmainW_78
	s_waitcnt lgkmcnt(0)

;     __device__ __forceinline__ void prep(int pm, int par, LAS unsigned char* lds) const { if (fold) prep_rowstats(stat, pm, par, lds); }
;     __device__ __forceinline__ void prep(int pm, int par, LAS unsigned char* lds) const { if (!ident) prep_rowstats(stat, pm, par, lds); }
;     __device__ __forceinline__ void prep(int pm, int par, LAS unsigned char* lds) const { prep_rowstats(stat, pm, par, lds); }
; #define G_STAGE(bufoff, gbase) do { _Pragma("unroll") for (int _i = 0; _i < 2; ++_i) \
;         __builtin_amdgcn_global_load_lds((const unsigned*)((const char*)(gbase) + voff[_i]), (LAS unsigned*)(lds + (bufoff) + ldsw + _i * 8192), 16, 0, 0); } while (0)
; #define G_LDA(dst, b, h) do { _Pragma("unroll") for (int m = 0; m < 4; ++m) _Pragma("unroll") for (int k = 0; k < 2; ++k) dst[m][k] = *(const LAS bf16x8*)(lds + G_SA(b, h) + aoff + m * 2048 + k * 1024); } while (0)
; #define G_LDB(dst, b, h) do { _Pragma("unroll") for (int n = 0; n < 2; ++n) _Pragma("unroll") for (int k = 0; k < 2; ++k) dst[n][k] = *(const LAS bf16x8*)(lds + G_SB(b, h) + boff + n * 2048 + k * 1024); } while (0)
; #define G_WAIT_V(n) asm volatile("s_waitcnt vmcnt(" #n ")" ::: "memory")
; #define G_WAIT_L(n) asm volatile("s_waitcnt lgkmcnt(" #n ")" ::: "memory")
; #define G_BAR __builtin_amdgcn_s_barrier()
; template <class Epi>
; __device__ __forceinline__ void gemm_phase(LAS unsigned char* lds, const bf16_t* Ag, const bf16_t* Btg, const int K, const int nM, const int nN, const Epi& E) {
;     ...
;             const char* a1 = cA + (size_t)(t + 1) * kstep;
;             const char* a2 = last ? nA : cA + (size_t)(t + 2) * kstep; const char* b2 = last ? nB : cB + (size_t)(t + 2) * kstep;
;             const char* a3 = a2 + kstep; const char* b3 = b2 + kstep;
;             if (last && has_next && pmn != pm) E.prep(pmn, par ^ 1, lds);
;             G_LDB(B0, 0, 0); G_SCHED; G_LDA(At, 0, 0); G_STAGE(G_SA(1, 1), a1 + hstep);
;             G_WAIT_L(8); G_BAR; G_WAIT_L(0); G_MMA(0, 0, At, B0); G_BAR; G_SCHED;
;             G_LDB(B1, 0, 1); G_STAGE(G_SB(0, 0), b2);
;             G_BAR; G_WAIT_L(0); G_MMA(0, 1, At, B1); G_BAR;
;             G_LDA(At, 0, 1); G_STAGE(G_SA(0, 0), a2);
;             G_BAR; G_WAIT_L(0); G_MMA(1, 0, At, B0); G_BAR; G_SCHED;
;             G_STAGE(G_SB(0, 1), b2 + hstep);
;             G_WAIT_V(6); G_BAR; G_MMA(1, 1, At, B1); G_BAR;
.LBB0_153:
	s_add_u32 s66, s64, 0x100
	s_addc_u32 s67, s65, 0
	s_and_b64 s[68:69], s[68:69], exec
	s_cselect_b32 s71, s67, s55
	s_cselect_b32 s70, s66, s54
	s_cselect_b32 s69, s61, s14
	s_cselect_b32 s68, s57, s15
	ds_read_b128 v[144:147], v217
	ds_read_b128 v[148:151], v217 offset:1024
	ds_read_b128 v[152:155], v217 offset:2048
	ds_read_b128 v[156:159], v217 offset:3072
.LmainW_153:
	s_add_i32 m0, s72, 0xc000
	ds_read_b128 v[160:163], v230
	ds_read_b128 v[164:167], v230 offset:1024
	ds_read_b128 v[168:171], v230 offset:2048
	ds_read_b128 v[172:175], v230 offset:3072
	ds_read_b128 v[180:183], v230 offset:4096
	ds_read_b128 v[184:187], v230 offset:5120
	ds_read_b128 v[188:191], v230 offset:6144
	global_load_lds_dwordx4 v138, s[64:65]
	s_add_i32 m0, s72, 0xe000
	ds_read_b128 v[192:195], v230 offset:7168
	global_load_lds_dwordx4 v136, s[64:65]
	s_waitcnt lgkmcnt(8)
	s_barrier
	s_waitcnt lgkmcnt(0)
	s_waitcnt lgkmcnt(0)
	v_mfma_f32_16x16x32_bf16 v[132:135], v[144:147], v[160:163], v[132:135]
	v_mfma_f32_16x16x32_bf16 v[128:131], v[152:155], v[160:163], v[128:131]
	v_mfma_f32_16x16x32_bf16 v[116:119], v[144:147], v[168:171], v[116:119]
	v_mfma_f32_16x16x32_bf16 v[112:115], v[152:155], v[168:171], v[112:115]
	v_mfma_f32_16x16x32_bf16 v[100:103], v[144:147], v[180:183], v[100:103]
	v_mfma_f32_16x16x32_bf16 v[96:99], v[152:155], v[180:183], v[96:99]
	v_mfma_f32_16x16x32_bf16 v[84:87], v[144:147], v[188:191], v[84:87]
	v_mfma_f32_16x16x32_bf16 v[80:83], v[152:155], v[188:191], v[80:83]
	v_mfma_f32_16x16x32_bf16 v[132:135], v[148:151], v[164:167], v[132:135]
	v_mfma_f32_16x16x32_bf16 v[128:131], v[156:159], v[164:167], v[128:131]
	v_mfma_f32_16x16x32_bf16 v[116:119], v[148:151], v[172:175], v[116:119]
	v_mfma_f32_16x16x32_bf16 v[112:115], v[156:159], v[172:175], v[112:115]
	v_mfma_f32_16x16x32_bf16 v[100:103], v[148:151], v[184:187], v[100:103]
	v_mfma_f32_16x16x32_bf16 v[96:99], v[156:159], v[184:187], v[96:99]
	v_mfma_f32_16x16x32_bf16 v[84:87], v[148:151], v[192:195], v[84:87]
	v_mfma_f32_16x16x32_bf16 v[80:83], v[156:159], v[192:195], v[80:83]
	s_barrier
	s_add_i32 m0, s21, 0x10000
	ds_read_b128 v[232:235], v217 offset:16384
	ds_read_b128 v[236:239], v217 offset:17408
	ds_read_b128 v[240:243], v217 offset:18432
	global_load_lds_dwordx4 v0, s[68:69]
	s_add_i32 m0, s21, 0x12000
	ds_read_b128 v[244:247], v217 offset:19456
	global_load_lds_dwordx4 v2, s[68:69]
	s_barrier
	s_waitcnt lgkmcnt(0)
	s_waitcnt lgkmcnt(0)
	v_mfma_f32_16x16x32_bf16 v[124:127], v[232:235], v[160:163], v[124:127]
	v_mfma_f32_16x16x32_bf16 v[120:123], v[240:243], v[160:163], v[120:123]
	v_mfma_f32_16x16x32_bf16 v[108:111], v[232:235], v[168:171], v[108:111]
	v_mfma_f32_16x16x32_bf16 v[104:107], v[240:243], v[168:171], v[104:107]
	v_mfma_f32_16x16x32_bf16 v[92:95], v[232:235], v[180:183], v[92:95]
	v_mfma_f32_16x16x32_bf16 v[88:91], v[240:243], v[180:183], v[88:91]
	v_mfma_f32_16x16x32_bf16 v[76:79], v[232:235], v[188:191], v[76:79]
	v_mfma_f32_16x16x32_bf16 v[72:75], v[240:243], v[188:191], v[72:75]
	v_mfma_f32_16x16x32_bf16 v[124:127], v[236:239], v[164:167], v[124:127]
	v_mfma_f32_16x16x32_bf16 v[120:123], v[244:247], v[164:167], v[120:123]
	v_mfma_f32_16x16x32_bf16 v[108:111], v[236:239], v[172:175], v[108:111]
	v_mfma_f32_16x16x32_bf16 v[104:107], v[244:247], v[172:175], v[104:107]
	v_mfma_f32_16x16x32_bf16 v[92:95], v[236:239], v[184:187], v[92:95]
	v_mfma_f32_16x16x32_bf16 v[88:91], v[244:247], v[184:187], v[88:91]
	v_mfma_f32_16x16x32_bf16 v[76:79], v[236:239], v[192:195], v[76:79]
	v_mfma_f32_16x16x32_bf16 v[72:75], v[244:247], v[192:195], v[72:75]
	s_mov_b32 m0, s72
	s_barrier
	ds_read_b128 v[160:163], v230 offset:16384
	ds_read_b128 v[164:167], v230 offset:17408
	ds_read_b128 v[168:171], v230 offset:18432
	ds_read_b128 v[172:175], v230 offset:19456
	ds_read_b128 v[180:183], v230 offset:20480
	ds_read_b128 v[184:187], v230 offset:21504
	ds_read_b128 v[188:191], v230 offset:22528
	global_load_lds_dwordx4 v0, s[70:71]
	s_mov_b32 m0, s73
	ds_read_b128 v[192:195], v230 offset:23552
	global_load_lds_dwordx4 v2, s[70:71]
	s_waitcnt vmcnt(10)
	s_barrier
	s_waitcnt lgkmcnt(0)
	s_waitcnt lgkmcnt(0)
	v_mfma_f32_16x16x32_bf16 v[68:71], v[144:147], v[160:163], v[68:71]
	v_mfma_f32_16x16x32_bf16 v[64:67], v[152:155], v[160:163], v[64:67]
	v_mfma_f32_16x16x32_bf16 v[52:55], v[144:147], v[168:171], v[52:55]
	v_mfma_f32_16x16x32_bf16 v[48:51], v[152:155], v[168:171], v[48:51]
	v_mfma_f32_16x16x32_bf16 v[36:39], v[144:147], v[180:183], v[36:39]
	v_mfma_f32_16x16x32_bf16 v[32:35], v[152:155], v[180:183], v[32:35]
	v_mfma_f32_16x16x32_bf16 v[20:23], v[144:147], v[188:191], v[20:23]
	v_mfma_f32_16x16x32_bf16 v[16:19], v[152:155], v[188:191], v[16:19]
	v_mfma_f32_16x16x32_bf16 v[68:71], v[148:151], v[164:167], v[68:71]
	v_mfma_f32_16x16x32_bf16 v[64:67], v[156:159], v[164:167], v[64:67]
	v_mfma_f32_16x16x32_bf16 v[52:55], v[148:151], v[172:175], v[52:55]
	v_mfma_f32_16x16x32_bf16 v[48:51], v[156:159], v[172:175], v[48:51]
	v_mfma_f32_16x16x32_bf16 v[36:39], v[148:151], v[184:187], v[36:39]
	v_mfma_f32_16x16x32_bf16 v[32:35], v[156:159], v[184:187], v[32:35]
	v_mfma_f32_16x16x32_bf16 v[20:23], v[148:151], v[192:195], v[20:23]
	v_mfma_f32_16x16x32_bf16 v[16:19], v[156:159], v[192:195], v[16:19]
	s_barrier
	ds_read_b128 v[144:147], v217 offset:32768
	ds_read_b128 v[148:151], v217 offset:33792
	ds_read_b128 v[152:155], v217 offset:34816
	ds_read_b128 v[156:159], v217 offset:35840
	s_add_i32 m0, s21, 0x14000
	s_add_u32 s64, s68, 0x40000
	s_addc_u32 s65, s69, 0
	global_load_lds_dwordx4 v0, s[64:65]
	s_add_i32 m0, s21, 0x16000
	s_add_u32 s98, s70, 0x40000
	s_addc_u32 s99, s71, 0
	global_load_lds_dwordx4 v2, s[64:65]
	s_waitcnt vmcnt(6)
	s_barrier
; #define G_STAGE(bufoff, gbase) do { _Pragma("unroll") for (int _i = 0; _i < 2; ++_i) \
;         __builtin_amdgcn_global_load_lds((const unsigned*)((const char*)(gbase) + voff[_i]), (LAS unsigned*)(lds + (bufoff) + ldsw + _i * 8192), 16, 0, 0); } while (0)
; #define G_LDA(dst, b, h) do { _Pragma("unroll") for (int m = 0; m < 4; ++m) _Pragma("unroll") for (int k = 0; k < 2; ++k) dst[m][k] = *(const LAS bf16x8*)(lds + G_SA(b, h) + aoff + m * 2048 + k * 1024); } while (0)
; #define G_LDB(dst, b, h) do { _Pragma("unroll") for (int n = 0; n < 2; ++n) _Pragma("unroll") for (int k = 0; k < 2; ++k) dst[n][k] = *(const LAS bf16x8*)(lds + G_SB(b, h) + boff + n * 2048 + k * 1024); } while (0)
; #define G_MMA(ai, bj, At, Bt) do { __builtin_amdgcn_s_setprio(1); _Pragma("unroll") for (int m = 0; m < 4; ++m) _Pragma("unroll") for (int n = 0; n < 2; ++n) _Pragma("unroll") for (int k = 0; k < 2; ++k) \
;         acc[ai][bj][m][n] = MFMA16(Bt[n][k], At[m][k], acc[ai][bj][m][n]); __builtin_amdgcn_s_setprio(0); } while (0)
; #define G_WAIT_V(n) asm volatile("s_waitcnt vmcnt(" #n ")" ::: "memory")
; #define G_WAIT_L(n) asm volatile("s_waitcnt lgkmcnt(" #n ")" ::: "memory")
; #define G_BAR __builtin_amdgcn_s_barrier()
; #define G_SCHED __builtin_amdgcn_sched_barrier(0)
; template <class Epi>
; __device__ __forceinline__ void gemm_phase(LAS unsigned char* lds, const bf16_t* Ag, const bf16_t* Btg, const int K, const int nM, const int nN, const Epi& E) {
;     ...
;             const char* a1 = cA + (size_t)(t + 1) * kstep;
;             const char* a2 = last ? nA : cA + (size_t)(t + 2) * kstep; const char* b2 = last ? nB : cB + (size_t)(t + 2) * kstep;
;             const char* a3 = a2 + kstep; const char* b3 = b2 + kstep;
;     ...
;             G_WAIT_V(6); G_BAR; G_MMA(1, 1, At, B1); G_BAR;
;             G_LDB(B0, 1, 0); G_SCHED; G_LDA(At, 1, 0); G_STAGE(G_SA(0, 1), a2 + hstep);
;             G_WAIT_L(8); G_BAR; G_WAIT_L(0); G_MMA(0, 0, At, B0); G_BAR; G_SCHED;
;             G_LDB(B1, 1, 1); G_STAGE(G_SB(1, 0), b3);
;             G_BAR; G_WAIT_L(0); G_MMA(0, 1, At, B1); G_BAR;
;             G_LDA(At, 1, 1); G_STAGE(G_SA(1, 0), a3);
;             G_BAR; G_WAIT_L(0); G_MMA(1, 0, At, B0); G_BAR; G_SCHED;
;             G_STAGE(G_SB(1, 1), b3 + hstep);
;             G_WAIT_V(6); G_BAR; G_MMA(1, 1, At, B1); G_BAR;
	v_mfma_f32_16x16x32_bf16 v[60:63], v[232:235], v[160:163], v[60:63]
	v_mfma_f32_16x16x32_bf16 v[56:59], v[240:243], v[160:163], v[56:59]
	v_mfma_f32_16x16x32_bf16 v[44:47], v[232:235], v[168:171], v[44:47]
	v_mfma_f32_16x16x32_bf16 v[40:43], v[240:243], v[168:171], v[40:43]
	v_mfma_f32_16x16x32_bf16 v[28:31], v[232:235], v[180:183], v[28:31]
	v_mfma_f32_16x16x32_bf16 v[24:27], v[240:243], v[180:183], v[24:27]
	v_mfma_f32_16x16x32_bf16 v[12:15], v[232:235], v[188:191], v[12:15]
	v_mfma_f32_16x16x32_bf16 v[8:11], v[240:243], v[188:191], v[8:11]
	v_mfma_f32_16x16x32_bf16 v[60:63], v[236:239], v[164:167], v[60:63]
	v_mfma_f32_16x16x32_bf16 v[56:59], v[244:247], v[164:167], v[56:59]
	v_mfma_f32_16x16x32_bf16 v[44:47], v[236:239], v[172:175], v[44:47]
	v_mfma_f32_16x16x32_bf16 v[40:43], v[244:247], v[172:175], v[40:43]
	v_mfma_f32_16x16x32_bf16 v[28:31], v[236:239], v[184:187], v[28:31]
	v_mfma_f32_16x16x32_bf16 v[24:27], v[244:247], v[184:187], v[24:27]
	v_mfma_f32_16x16x32_bf16 v[12:15], v[236:239], v[192:195], v[12:15]
	v_mfma_f32_16x16x32_bf16 v[8:11], v[244:247], v[192:195], v[8:11]
	s_barrier
	s_mov_b32 m0, s74
	ds_read_b128 v[160:163], v230 offset:32768
	ds_read_b128 v[164:167], v230 offset:33792
	ds_read_b128 v[168:171], v230 offset:34816
	ds_read_b128 v[172:175], v230 offset:35840
	ds_read_b128 v[180:183], v230 offset:36864
	ds_read_b128 v[184:187], v230 offset:37888
	ds_read_b128 v[188:191], v230 offset:38912
	global_load_lds_dwordx4 v0, s[98:99]
	s_mov_b32 m0, s75
	ds_read_b128 v[192:195], v230 offset:39936
	global_load_lds_dwordx4 v2, s[98:99]
	s_waitcnt lgkmcnt(8)
	s_barrier
	s_waitcnt lgkmcnt(0)
	s_waitcnt lgkmcnt(0)
	v_mfma_f32_16x16x32_bf16 v[132:135], v[144:147], v[160:163], v[132:135]
	v_mfma_f32_16x16x32_bf16 v[128:131], v[152:155], v[160:163], v[128:131]
	v_mfma_f32_16x16x32_bf16 v[116:119], v[144:147], v[168:171], v[116:119]
	v_mfma_f32_16x16x32_bf16 v[112:115], v[152:155], v[168:171], v[112:115]
	v_mfma_f32_16x16x32_bf16 v[100:103], v[144:147], v[180:183], v[100:103]
	v_mfma_f32_16x16x32_bf16 v[96:99], v[152:155], v[180:183], v[96:99]
	v_mfma_f32_16x16x32_bf16 v[84:87], v[144:147], v[188:191], v[84:87]
	v_mfma_f32_16x16x32_bf16 v[80:83], v[152:155], v[188:191], v[80:83]
	v_mfma_f32_16x16x32_bf16 v[132:135], v[148:151], v[164:167], v[132:135]
	v_mfma_f32_16x16x32_bf16 v[128:131], v[156:159], v[164:167], v[128:131]
	v_mfma_f32_16x16x32_bf16 v[116:119], v[148:151], v[172:175], v[116:119]
	v_mfma_f32_16x16x32_bf16 v[112:115], v[156:159], v[172:175], v[112:115]
	v_mfma_f32_16x16x32_bf16 v[100:103], v[148:151], v[184:187], v[100:103]
	v_mfma_f32_16x16x32_bf16 v[96:99], v[156:159], v[184:187], v[96:99]
	v_mfma_f32_16x16x32_bf16 v[84:87], v[148:151], v[192:195], v[84:87]
	v_mfma_f32_16x16x32_bf16 v[80:83], v[156:159], v[192:195], v[80:83]
	s_barrier
	s_add_i32 m0, s21, 0x18000
	ds_read_b128 v[232:235], v217 offset:49152
	ds_read_b128 v[236:239], v217 offset:50176
	ds_read_b128 v[240:243], v217 offset:51200
	s_add_u32 s98, s68, 0x80
	s_addc_u32 s99, s69, 0
	global_load_lds_dwordx4 v0, s[98:99]
	s_add_i32 m0, s21, 0x1a000
	ds_read_b128 v[244:247], v217 offset:52224
	global_load_lds_dwordx4 v2, s[98:99]
	s_barrier
	s_waitcnt lgkmcnt(0)
	s_waitcnt lgkmcnt(0)
	v_mfma_f32_16x16x32_bf16 v[124:127], v[232:235], v[160:163], v[124:127]
	v_mfma_f32_16x16x32_bf16 v[120:123], v[240:243], v[160:163], v[120:123]
	v_mfma_f32_16x16x32_bf16 v[108:111], v[232:235], v[168:171], v[108:111]
	v_mfma_f32_16x16x32_bf16 v[104:107], v[240:243], v[168:171], v[104:107]
	v_mfma_f32_16x16x32_bf16 v[92:95], v[232:235], v[180:183], v[92:95]
	v_mfma_f32_16x16x32_bf16 v[88:91], v[240:243], v[180:183], v[88:91]
	v_mfma_f32_16x16x32_bf16 v[76:79], v[232:235], v[188:191], v[76:79]
	v_mfma_f32_16x16x32_bf16 v[72:75], v[240:243], v[188:191], v[72:75]
	v_mfma_f32_16x16x32_bf16 v[124:127], v[236:239], v[164:167], v[124:127]
	v_mfma_f32_16x16x32_bf16 v[120:123], v[244:247], v[164:167], v[120:123]
	v_mfma_f32_16x16x32_bf16 v[108:111], v[236:239], v[172:175], v[108:111]
	v_mfma_f32_16x16x32_bf16 v[104:107], v[244:247], v[172:175], v[104:107]
	v_mfma_f32_16x16x32_bf16 v[92:95], v[236:239], v[184:187], v[92:95]
	v_mfma_f32_16x16x32_bf16 v[88:91], v[244:247], v[184:187], v[88:91]
	v_mfma_f32_16x16x32_bf16 v[76:79], v[236:239], v[192:195], v[76:79]
	v_mfma_f32_16x16x32_bf16 v[72:75], v[244:247], v[192:195], v[72:75]
	s_mov_b32 m0, s76
	s_barrier
	ds_read_b128 v[160:163], v230 offset:49152
	ds_read_b128 v[164:167], v230 offset:50176
	ds_read_b128 v[168:171], v230 offset:51200
	ds_read_b128 v[172:175], v230 offset:52224
	ds_read_b128 v[180:183], v230 offset:53248
	ds_read_b128 v[184:187], v230 offset:54272
	ds_read_b128 v[188:191], v230 offset:55296
	s_add_u32 s98, s70, 0x80
	s_addc_u32 s99, s71, 0
	global_load_lds_dwordx4 v0, s[98:99]
	s_mov_b32 m0, s77
	ds_read_b128 v[192:195], v230 offset:56320
	global_load_lds_dwordx4 v2, s[98:99]
	s_waitcnt vmcnt(10)
	s_barrier
	s_waitcnt lgkmcnt(0)
	s_waitcnt lgkmcnt(0)
	v_mfma_f32_16x16x32_bf16 v[68:71], v[144:147], v[160:163], v[68:71]
	v_mfma_f32_16x16x32_bf16 v[64:67], v[152:155], v[160:163], v[64:67]
	v_mfma_f32_16x16x32_bf16 v[52:55], v[144:147], v[168:171], v[52:55]
	v_mfma_f32_16x16x32_bf16 v[48:51], v[152:155], v[168:171], v[48:51]
	v_mfma_f32_16x16x32_bf16 v[36:39], v[144:147], v[180:183], v[36:39]
	v_mfma_f32_16x16x32_bf16 v[32:35], v[152:155], v[180:183], v[32:35]
	v_mfma_f32_16x16x32_bf16 v[20:23], v[144:147], v[188:191], v[20:23]
	v_mfma_f32_16x16x32_bf16 v[16:19], v[152:155], v[188:191], v[16:19]
	v_mfma_f32_16x16x32_bf16 v[68:71], v[148:151], v[164:167], v[68:71]
	v_mfma_f32_16x16x32_bf16 v[64:67], v[156:159], v[164:167], v[64:67]
	v_mfma_f32_16x16x32_bf16 v[52:55], v[148:151], v[172:175], v[52:55]
	v_mfma_f32_16x16x32_bf16 v[48:51], v[156:159], v[172:175], v[48:51]
	v_mfma_f32_16x16x32_bf16 v[36:39], v[148:151], v[184:187], v[36:39]
	v_mfma_f32_16x16x32_bf16 v[32:35], v[156:159], v[184:187], v[32:35]
	v_mfma_f32_16x16x32_bf16 v[20:23], v[148:151], v[192:195], v[20:23]
	v_mfma_f32_16x16x32_bf16 v[16:19], v[156:159], v[192:195], v[16:19]
	s_barrier
	s_add_i32 m0, s21, 0x1c000
	s_add_u32 s64, s68, 0x40080
	s_addc_u32 s65, s69, 0
	global_load_lds_dwordx4 v0, s[64:65]
	s_add_i32 m0, s21, 0x1e000
	s_add_i32 s42, s42, 2
	global_load_lds_dwordx4 v2, s[64:65]
	s_add_u32 s57, s57, 0x100
	s_addc_u32 s61, s61, 0
	s_mov_b64 s[64:65], s[66:67]
	s_cmp_gt_u32 s42, 13
	s_cbranch_scc1 .LrotX_153
	ds_read_b128 v[144:147], v217
	ds_read_b128 v[148:151], v217 offset:1024
	ds_read_b128 v[152:155], v217 offset:2048
	ds_read_b128 v[156:159], v217 offset:3072
	s_cmp_lg_u32 s42, 12
	s_cselect_b64 s[68:69], -1, 0
	s_add_u32 s66, s64, 0x100
	s_addc_u32 s67, s65, 0
	s_and_b64 s[68:69], s[68:69], exec
	s_cselect_b32 s71, s67, s55
	s_cselect_b32 s70, s66, s54
	s_cselect_b32 s69, s61, s14
	s_cselect_b32 s68, s57, s15
; #define G_STAGE(bufoff, gbase) do { _Pragma("unroll") for (int _i = 0; _i < 2; ++_i) \
;         __builtin_amdgcn_global_load_lds((const unsigned*)((const char*)(gbase) + voff[_i]), (LAS unsigned*)(lds + (bufoff) + ldsw + _i * 8192), 16, 0, 0); } while (0)
; #define G_MMA(ai, bj, At, Bt) do { __builtin_amdgcn_s_setprio(1); _Pragma("unroll") for (int m = 0; m < 4; ++m) _Pragma("unroll") for (int n = 0; n < 2; ++n) _Pragma("unroll") for (int k = 0; k < 2; ++k) \
;         acc[ai][bj][m][n] = MFMA16(Bt[n][k], At[m][k], acc[ai][bj][m][n]); __builtin_amdgcn_s_setprio(0); } while (0)
; #define G_WAIT_V(n) asm volatile("s_waitcnt vmcnt(" #n ")" ::: "memory")
; #define G_BAR __builtin_amdgcn_s_barrier()
; template <class Epi>
; __device__ __forceinline__ void gemm_phase(LAS unsigned char* lds, const bf16_t* Ag, const bf16_t* Btg, const int K, const int nM, const int nN, const Epi& E) {
;     ...
;             G_STAGE(G_SB(1, 1), b3 + hstep);
;             G_WAIT_V(6); G_BAR; G_MMA(1, 1, At, B1); G_BAR;
;         }
.LrotX_153:
	s_waitcnt vmcnt(6)
	s_barrier
	v_mfma_f32_16x16x32_bf16 v[60:63], v[232:235], v[160:163], v[60:63]
	v_mfma_f32_16x16x32_bf16 v[56:59], v[240:243], v[160:163], v[56:59]
	v_mfma_f32_16x16x32_bf16 v[44:47], v[232:235], v[168:171], v[44:47]
	v_mfma_f32_16x16x32_bf16 v[40:43], v[240:243], v[168:171], v[40:43]
	v_mfma_f32_16x16x32_bf16 v[28:31], v[232:235], v[180:183], v[28:31]
	v_mfma_f32_16x16x32_bf16 v[24:27], v[240:243], v[180:183], v[24:27]
	v_mfma_f32_16x16x32_bf16 v[12:15], v[232:235], v[188:191], v[12:15]
	v_mfma_f32_16x16x32_bf16 v[8:11], v[240:243], v[188:191], v[8:11]
	v_mfma_f32_16x16x32_bf16 v[60:63], v[236:239], v[164:167], v[60:63]
	v_mfma_f32_16x16x32_bf16 v[56:59], v[244:247], v[164:167], v[56:59]
	v_mfma_f32_16x16x32_bf16 v[44:47], v[236:239], v[172:175], v[44:47]
	v_mfma_f32_16x16x32_bf16 v[40:43], v[244:247], v[172:175], v[40:43]
	v_mfma_f32_16x16x32_bf16 v[28:31], v[236:239], v[184:187], v[28:31]
	v_mfma_f32_16x16x32_bf16 v[24:27], v[244:247], v[184:187], v[24:27]
	v_mfma_f32_16x16x32_bf16 v[12:15], v[236:239], v[192:195], v[12:15]
	v_mfma_f32_16x16x32_bf16 v[8:11], v[244:247], v[192:195], v[8:11]
	s_cmp_gt_u32 s42, 13
	s_barrier
	s_cbranch_scc1 .LBB0_157
	s_cmp_lg_u32 s42, 12
	s_cbranch_scc1 .LmainW_153
	s_waitcnt lgkmcnt(0)

;     __device__ __forceinline__ void prep(int pm, int par, LAS unsigned char* lds) const { if (fold) prep_rowstats(stat, pm, par, lds); }
;     __device__ __forceinline__ void prep(int pm, int par, LAS unsigned char* lds) const { if (!ident) prep_rowstats(stat, pm, par, lds); }
;     __device__ __forceinline__ void prep(int pm, int par, LAS unsigned char* lds) const { prep_rowstats(stat, pm, par, lds); }
; #define G_STAGE(bufoff, gbase) do { _Pragma("unroll") for (int _i = 0; _i < 2; ++_i) \
;         __builtin_amdgcn_global_load_lds((const unsigned*)((const char*)(gbase) + voff[_i]), (LAS unsigned*)(lds + (bufoff) + ldsw + _i * 8192), 16, 0, 0); } while (0)
; #define G_LDA(dst, b, h) do { _Pragma("unroll") for (int m = 0; m < 4; ++m) _Pragma("unroll") for (int k = 0; k < 2; ++k) dst[m][k] = *(const LAS bf16x8*)(lds + G_SA(b, h) + aoff + m * 2048 + k * 1024); } while (0)
; #define G_LDB(dst, b, h) do { _Pragma("unroll") for (int n = 0; n < 2; ++n) _Pragma("unroll") for (int k = 0; k < 2; ++k) dst[n][k] = *(const LAS bf16x8*)(lds + G_SB(b, h) + boff + n * 2048 + k * 1024); } while (0)
; #define G_WAIT_V(n) asm volatile("s_waitcnt vmcnt(" #n ")" ::: "memory")
; #define G_WAIT_L(n) asm volatile("s_waitcnt lgkmcnt(" #n ")" ::: "memory")
; #define G_BAR __builtin_amdgcn_s_barrier()
; template <class Epi>
; __device__ __forceinline__ void gemm_phase(LAS unsigned char* lds, const bf16_t* Ag, const bf16_t* Btg, const int K, const int nM, const int nN, const Epi& E) {
;     ...
;             const char* a1 = cA + (size_t)(t + 1) * kstep;
;             const char* a2 = last ? nA : cA + (size_t)(t + 2) * kstep; const char* b2 = last ? nB : cB + (size_t)(t + 2) * kstep;
;             const char* a3 = a2 + kstep; const char* b3 = b2 + kstep;
;             if (last && has_next && pmn != pm) E.prep(pmn, par ^ 1, lds);
;             G_LDB(B0, 0, 0); G_SCHED; G_LDA(At, 0, 0); G_STAGE(G_SA(1, 1), a1 + hstep);
;             G_WAIT_L(8); G_BAR; G_WAIT_L(0); G_MMA(0, 0, At, B0); G_BAR; G_SCHED;
;             G_LDB(B1, 0, 1); G_STAGE(G_SB(0, 0), b2);
;             G_BAR; G_WAIT_L(0); G_MMA(0, 1, At, B1); G_BAR;
;             G_LDA(At, 0, 1); G_STAGE(G_SA(0, 0), a2);
;             G_BAR; G_WAIT_L(0); G_MMA(1, 0, At, B0); G_BAR; G_SCHED;
;             G_STAGE(G_SB(0, 1), b2 + hstep);
;             G_WAIT_V(6); G_BAR; G_MMA(1, 1, At, B1); G_BAR;
.LBB0_744:
	s_add_u32 s58, s56, 0x100
	s_addc_u32 s59, s57, 0
	s_and_b64 s[60:61], s[60:61], exec
	s_cselect_b32 s63, s59, s47
	s_cselect_b32 s62, s58, s46
	s_cselect_b32 s61, s78, s15
	s_cselect_b32 s60, s77, s49
	ds_read_b128 v[140:143], v217
	ds_read_b128 v[144:147], v217 offset:1024
	ds_read_b128 v[148:151], v217 offset:2048
	ds_read_b128 v[152:155], v217 offset:3072
.LmainW_744:
	s_add_i32 m0, s66, 0xc000
	ds_read_b128 v[156:159], v174
	ds_read_b128 v[160:163], v174 offset:1024
	ds_read_b128 v[180:183], v174 offset:2048
	ds_read_b128 v[184:187], v174 offset:3072
	ds_read_b128 v[188:191], v174 offset:4096
	ds_read_b128 v[192:195], v174 offset:5120
	ds_read_b128 v[222:225], v174 offset:6144
	global_load_lds_dwordx4 v138, s[56:57]
	s_add_i32 m0, s66, 0xe000
	ds_read_b128 v[226:229], v174 offset:7168
	global_load_lds_dwordx4 v136, s[56:57]
	s_waitcnt lgkmcnt(8)
	s_barrier
	s_waitcnt lgkmcnt(0)
	s_waitcnt lgkmcnt(0)
	v_mfma_f32_16x16x32_bf16 v[132:135], v[140:143], v[156:159], v[132:135]
	v_mfma_f32_16x16x32_bf16 v[128:131], v[148:151], v[156:159], v[128:131]
	v_mfma_f32_16x16x32_bf16 v[116:119], v[140:143], v[180:183], v[116:119]
	v_mfma_f32_16x16x32_bf16 v[112:115], v[148:151], v[180:183], v[112:115]
	v_mfma_f32_16x16x32_bf16 v[100:103], v[140:143], v[188:191], v[100:103]
	v_mfma_f32_16x16x32_bf16 v[96:99], v[148:151], v[188:191], v[96:99]
	v_mfma_f32_16x16x32_bf16 v[84:87], v[140:143], v[222:225], v[84:87]
	v_mfma_f32_16x16x32_bf16 v[80:83], v[148:151], v[222:225], v[80:83]
	v_mfma_f32_16x16x32_bf16 v[132:135], v[144:147], v[160:163], v[132:135]
	v_mfma_f32_16x16x32_bf16 v[128:131], v[152:155], v[160:163], v[128:131]
	v_mfma_f32_16x16x32_bf16 v[116:119], v[144:147], v[184:187], v[116:119]
	v_mfma_f32_16x16x32_bf16 v[112:115], v[152:155], v[184:187], v[112:115]
	v_mfma_f32_16x16x32_bf16 v[100:103], v[144:147], v[192:195], v[100:103]
	v_mfma_f32_16x16x32_bf16 v[96:99], v[152:155], v[192:195], v[96:99]
	v_mfma_f32_16x16x32_bf16 v[84:87], v[144:147], v[226:229], v[84:87]
	v_mfma_f32_16x16x32_bf16 v[80:83], v[152:155], v[226:229], v[80:83]
	s_barrier
	s_add_i32 m0, s65, 0x10000
	ds_read_b128 v[230:233], v217 offset:16384
	ds_read_b128 v[234:237], v217 offset:17408
	ds_read_b128 v[238:241], v217 offset:18432
	global_load_lds_dwordx4 v0, s[60:61]
	s_add_i32 m0, s65, 0x12000
	ds_read_b128 v[242:245], v217 offset:19456
	global_load_lds_dwordx4 v2, s[60:61]
	s_barrier
	s_waitcnt lgkmcnt(0)
	s_waitcnt lgkmcnt(0)
	v_mfma_f32_16x16x32_bf16 v[124:127], v[230:233], v[156:159], v[124:127]
	v_mfma_f32_16x16x32_bf16 v[120:123], v[238:241], v[156:159], v[120:123]
	v_mfma_f32_16x16x32_bf16 v[108:111], v[230:233], v[180:183], v[108:111]
	v_mfma_f32_16x16x32_bf16 v[104:107], v[238:241], v[180:183], v[104:107]
	v_mfma_f32_16x16x32_bf16 v[92:95], v[230:233], v[188:191], v[92:95]
	v_mfma_f32_16x16x32_bf16 v[88:91], v[238:241], v[188:191], v[88:91]
	v_mfma_f32_16x16x32_bf16 v[76:79], v[230:233], v[222:225], v[76:79]
	v_mfma_f32_16x16x32_bf16 v[72:75], v[238:241], v[222:225], v[72:75]
	v_mfma_f32_16x16x32_bf16 v[124:127], v[234:237], v[160:163], v[124:127]
	v_mfma_f32_16x16x32_bf16 v[120:123], v[242:245], v[160:163], v[120:123]
	v_mfma_f32_16x16x32_bf16 v[108:111], v[234:237], v[184:187], v[108:111]
	v_mfma_f32_16x16x32_bf16 v[104:107], v[242:245], v[184:187], v[104:107]
	v_mfma_f32_16x16x32_bf16 v[92:95], v[234:237], v[192:195], v[92:95]
	v_mfma_f32_16x16x32_bf16 v[88:91], v[242:245], v[192:195], v[88:91]
	v_mfma_f32_16x16x32_bf16 v[76:79], v[234:237], v[226:229], v[76:79]
	v_mfma_f32_16x16x32_bf16 v[72:75], v[242:245], v[226:229], v[72:75]
	s_mov_b32 m0, s66
	s_barrier
	ds_read_b128 v[156:159], v174 offset:16384
	ds_read_b128 v[160:163], v174 offset:17408
	ds_read_b128 v[180:183], v174 offset:18432
	ds_read_b128 v[184:187], v174 offset:19456
	ds_read_b128 v[188:191], v174 offset:20480
	ds_read_b128 v[192:195], v174 offset:21504
	ds_read_b128 v[222:225], v174 offset:22528
	global_load_lds_dwordx4 v0, s[62:63]
	s_mov_b32 m0, s67
	ds_read_b128 v[226:229], v174 offset:23552
	global_load_lds_dwordx4 v2, s[62:63]
	s_waitcnt vmcnt(10)
	s_barrier
	s_waitcnt lgkmcnt(0)
	s_waitcnt lgkmcnt(0)
	v_mfma_f32_16x16x32_bf16 v[68:71], v[140:143], v[156:159], v[68:71]
	v_mfma_f32_16x16x32_bf16 v[64:67], v[148:151], v[156:159], v[64:67]
	v_mfma_f32_16x16x32_bf16 v[52:55], v[140:143], v[180:183], v[52:55]
	v_mfma_f32_16x16x32_bf16 v[48:51], v[148:151], v[180:183], v[48:51]
	v_mfma_f32_16x16x32_bf16 v[36:39], v[140:143], v[188:191], v[36:39]
	v_mfma_f32_16x16x32_bf16 v[32:35], v[148:151], v[188:191], v[32:35]
	v_mfma_f32_16x16x32_bf16 v[20:23], v[140:143], v[222:225], v[20:23]
	v_mfma_f32_16x16x32_bf16 v[16:19], v[148:151], v[222:225], v[16:19]
	v_mfma_f32_16x16x32_bf16 v[68:71], v[144:147], v[160:163], v[68:71]
	v_mfma_f32_16x16x32_bf16 v[64:67], v[152:155], v[160:163], v[64:67]
	v_mfma_f32_16x16x32_bf16 v[52:55], v[144:147], v[184:187], v[52:55]
	v_mfma_f32_16x16x32_bf16 v[48:51], v[152:155], v[184:187], v[48:51]
	v_mfma_f32_16x16x32_bf16 v[36:39], v[144:147], v[192:195], v[36:39]
	v_mfma_f32_16x16x32_bf16 v[32:35], v[152:155], v[192:195], v[32:35]
	v_mfma_f32_16x16x32_bf16 v[20:23], v[144:147], v[226:229], v[20:23]
	v_mfma_f32_16x16x32_bf16 v[16:19], v[152:155], v[226:229], v[16:19]
	s_barrier
	ds_read_b128 v[140:143], v217 offset:32768
	ds_read_b128 v[144:147], v217 offset:33792
	ds_read_b128 v[148:151], v217 offset:34816
	ds_read_b128 v[152:155], v217 offset:35840
	s_add_i32 m0, s65, 0x14000
	s_add_u32 s56, s60, 0x100000
	s_addc_u32 s57, s61, 0
	global_load_lds_dwordx4 v0, s[56:57]
	s_add_i32 m0, s65, 0x16000
	s_add_u32 s98, s62, 0x100000
	s_addc_u32 s99, s63, 0
	global_load_lds_dwordx4 v2, s[56:57]
	s_waitcnt vmcnt(6)
	s_barrier
; #define G_STAGE(bufoff, gbase) do { _Pragma("unroll") for (int _i = 0; _i < 2; ++_i) \
;         __builtin_amdgcn_global_load_lds((const unsigned*)((const char*)(gbase) + voff[_i]), (LAS unsigned*)(lds + (bufoff) + ldsw + _i * 8192), 16, 0, 0); } while (0)
; #define G_LDA(dst, b, h) do { _Pragma("unroll") for (int m = 0; m < 4; ++m) _Pragma("unroll") for (int k = 0; k < 2; ++k) dst[m][k] = *(const LAS bf16x8*)(lds + G_SA(b, h) + aoff + m * 2048 + k * 1024); } while (0)
; #define G_LDB(dst, b, h) do { _Pragma("unroll") for (int n = 0; n < 2; ++n) _Pragma("unroll") for (int k = 0; k < 2; ++k) dst[n][k] = *(const LAS bf16x8*)(lds + G_SB(b, h) + boff + n * 2048 + k * 1024); } while (0)
; #define G_MMA(ai, bj, At, Bt) do { __builtin_amdgcn_s_setprio(1); _Pragma("unroll") for (int m = 0; m < 4; ++m) _Pragma("unroll") for (int n = 0; n < 2; ++n) _Pragma("unroll") for (int k = 0; k < 2; ++k) \
;         acc[ai][bj][m][n] = MFMA16(Bt[n][k], At[m][k], acc[ai][bj][m][n]); __builtin_amdgcn_s_setprio(0); } while (0)
; #define G_WAIT_V(n) asm volatile("s_waitcnt vmcnt(" #n ")" ::: "memory")
; #define G_WAIT_L(n) asm volatile("s_waitcnt lgkmcnt(" #n ")" ::: "memory")
; #define G_BAR __builtin_amdgcn_s_barrier()
; #define G_SCHED __builtin_amdgcn_sched_barrier(0)
; template <class Epi>
; __device__ __forceinline__ void gemm_phase(LAS unsigned char* lds, const bf16_t* Ag, const bf16_t* Btg, const int K, const int nM, const int nN, const Epi& E) {
;     ...
;             const char* a1 = cA + (size_t)(t + 1) * kstep;
;             const char* a2 = last ? nA : cA + (size_t)(t + 2) * kstep; const char* b2 = last ? nB : cB + (size_t)(t + 2) * kstep;
;             const char* a3 = a2 + kstep; const char* b3 = b2 + kstep;
;     ...
;             G_WAIT_V(6); G_BAR; G_MMA(1, 1, At, B1); G_BAR;
;             G_LDB(B0, 1, 0); G_SCHED; G_LDA(At, 1, 0); G_STAGE(G_SA(0, 1), a2 + hstep);
;             G_WAIT_L(8); G_BAR; G_WAIT_L(0); G_MMA(0, 0, At, B0); G_BAR; G_SCHED;
;             G_LDB(B1, 1, 1); G_STAGE(G_SB(1, 0), b3);
;             G_BAR; G_WAIT_L(0); G_MMA(0, 1, At, B1); G_BAR;
;             G_LDA(At, 1, 1); G_STAGE(G_SA(1, 0), a3);
;             G_BAR; G_WAIT_L(0); G_MMA(1, 0, At, B0); G_BAR; G_SCHED;
;             G_STAGE(G_SB(1, 1), b3 + hstep);
;             G_WAIT_V(6); G_BAR; G_MMA(1, 1, At, B1); G_BAR;
	v_mfma_f32_16x16x32_bf16 v[60:63], v[230:233], v[156:159], v[60:63]
	v_mfma_f32_16x16x32_bf16 v[56:59], v[238:241], v[156:159], v[56:59]
	v_mfma_f32_16x16x32_bf16 v[44:47], v[230:233], v[180:183], v[44:47]
	v_mfma_f32_16x16x32_bf16 v[40:43], v[238:241], v[180:183], v[40:43]
	v_mfma_f32_16x16x32_bf16 v[28:31], v[230:233], v[188:191], v[28:31]
	v_mfma_f32_16x16x32_bf16 v[24:27], v[238:241], v[188:191], v[24:27]
	v_mfma_f32_16x16x32_bf16 v[12:15], v[230:233], v[222:225], v[12:15]
	v_mfma_f32_16x16x32_bf16 v[8:11], v[238:241], v[222:225], v[8:11]
	v_mfma_f32_16x16x32_bf16 v[60:63], v[234:237], v[160:163], v[60:63]
	v_mfma_f32_16x16x32_bf16 v[56:59], v[242:245], v[160:163], v[56:59]
	v_mfma_f32_16x16x32_bf16 v[44:47], v[234:237], v[184:187], v[44:47]
	v_mfma_f32_16x16x32_bf16 v[40:43], v[242:245], v[184:187], v[40:43]
	v_mfma_f32_16x16x32_bf16 v[28:31], v[234:237], v[192:195], v[28:31]
	v_mfma_f32_16x16x32_bf16 v[24:27], v[242:245], v[192:195], v[24:27]
	v_mfma_f32_16x16x32_bf16 v[12:15], v[234:237], v[226:229], v[12:15]
	v_mfma_f32_16x16x32_bf16 v[8:11], v[242:245], v[226:229], v[8:11]
	s_barrier
	s_mov_b32 m0, s68
	ds_read_b128 v[156:159], v174 offset:32768
	ds_read_b128 v[160:163], v174 offset:33792
	ds_read_b128 v[180:183], v174 offset:34816
	ds_read_b128 v[184:187], v174 offset:35840
	ds_read_b128 v[188:191], v174 offset:36864
	ds_read_b128 v[192:195], v174 offset:37888
	ds_read_b128 v[222:225], v174 offset:38912
	global_load_lds_dwordx4 v0, s[98:99]
	s_mov_b32 m0, s69
	ds_read_b128 v[226:229], v174 offset:39936
	global_load_lds_dwordx4 v2, s[98:99]
	s_waitcnt lgkmcnt(8)
	s_barrier
	s_waitcnt lgkmcnt(0)
	s_waitcnt lgkmcnt(0)
	v_mfma_f32_16x16x32_bf16 v[132:135], v[140:143], v[156:159], v[132:135]
	v_mfma_f32_16x16x32_bf16 v[128:131], v[148:151], v[156:159], v[128:131]
	v_mfma_f32_16x16x32_bf16 v[116:119], v[140:143], v[180:183], v[116:119]
	v_mfma_f32_16x16x32_bf16 v[112:115], v[148:151], v[180:183], v[112:115]
	v_mfma_f32_16x16x32_bf16 v[100:103], v[140:143], v[188:191], v[100:103]
	v_mfma_f32_16x16x32_bf16 v[96:99], v[148:151], v[188:191], v[96:99]
	v_mfma_f32_16x16x32_bf16 v[84:87], v[140:143], v[222:225], v[84:87]
	v_mfma_f32_16x16x32_bf16 v[80:83], v[148:151], v[222:225], v[80:83]
	v_mfma_f32_16x16x32_bf16 v[132:135], v[144:147], v[160:163], v[132:135]
	v_mfma_f32_16x16x32_bf16 v[128:131], v[152:155], v[160:163], v[128:131]
	v_mfma_f32_16x16x32_bf16 v[116:119], v[144:147], v[184:187], v[116:119]
	v_mfma_f32_16x16x32_bf16 v[112:115], v[152:155], v[184:187], v[112:115]
	v_mfma_f32_16x16x32_bf16 v[100:103], v[144:147], v[192:195], v[100:103]
	v_mfma_f32_16x16x32_bf16 v[96:99], v[152:155], v[192:195], v[96:99]
	v_mfma_f32_16x16x32_bf16 v[84:87], v[144:147], v[226:229], v[84:87]
	v_mfma_f32_16x16x32_bf16 v[80:83], v[152:155], v[226:229], v[80:83]
	s_barrier
	s_add_i32 m0, s65, 0x18000
	ds_read_b128 v[230:233], v217 offset:49152
	ds_read_b128 v[234:237], v217 offset:50176
	ds_read_b128 v[238:241], v217 offset:51200
	s_add_u32 s98, s60, 0x80
	s_addc_u32 s99, s61, 0
	global_load_lds_dwordx4 v0, s[98:99]
	s_add_i32 m0, s65, 0x1a000
	ds_read_b128 v[242:245], v217 offset:52224
	global_load_lds_dwordx4 v2, s[98:99]
	s_barrier
	s_waitcnt lgkmcnt(0)
	s_waitcnt lgkmcnt(0)
	v_mfma_f32_16x16x32_bf16 v[124:127], v[230:233], v[156:159], v[124:127]
	v_mfma_f32_16x16x32_bf16 v[120:123], v[238:241], v[156:159], v[120:123]
	v_mfma_f32_16x16x32_bf16 v[108:111], v[230:233], v[180:183], v[108:111]
	v_mfma_f32_16x16x32_bf16 v[104:107], v[238:241], v[180:183], v[104:107]
	v_mfma_f32_16x16x32_bf16 v[92:95], v[230:233], v[188:191], v[92:95]
	v_mfma_f32_16x16x32_bf16 v[88:91], v[238:241], v[188:191], v[88:91]
	v_mfma_f32_16x16x32_bf16 v[76:79], v[230:233], v[222:225], v[76:79]
	v_mfma_f32_16x16x32_bf16 v[72:75], v[238:241], v[222:225], v[72:75]
	v_mfma_f32_16x16x32_bf16 v[124:127], v[234:237], v[160:163], v[124:127]
	v_mfma_f32_16x16x32_bf16 v[120:123], v[242:245], v[160:163], v[120:123]
	v_mfma_f32_16x16x32_bf16 v[108:111], v[234:237], v[184:187], v[108:111]
	v_mfma_f32_16x16x32_bf16 v[104:107], v[242:245], v[184:187], v[104:107]
	v_mfma_f32_16x16x32_bf16 v[92:95], v[234:237], v[192:195], v[92:95]
	v_mfma_f32_16x16x32_bf16 v[88:91], v[242:245], v[192:195], v[88:91]
	v_mfma_f32_16x16x32_bf16 v[76:79], v[234:237], v[226:229], v[76:79]
	v_mfma_f32_16x16x32_bf16 v[72:75], v[242:245], v[226:229], v[72:75]
	s_mov_b32 m0, s70
	s_barrier
	ds_read_b128 v[156:159], v174 offset:49152
	ds_read_b128 v[160:163], v174 offset:50176
	ds_read_b128 v[180:183], v174 offset:51200
	ds_read_b128 v[184:187], v174 offset:52224
	ds_read_b128 v[188:191], v174 offset:53248
	ds_read_b128 v[192:195], v174 offset:54272
	ds_read_b128 v[222:225], v174 offset:55296
	s_add_u32 s98, s62, 0x80
	s_addc_u32 s99, s63, 0
	global_load_lds_dwordx4 v0, s[98:99]
	s_mov_b32 m0, s71
	ds_read_b128 v[226:229], v174 offset:56320
	global_load_lds_dwordx4 v2, s[98:99]
	s_waitcnt vmcnt(10)
	s_barrier
	s_waitcnt lgkmcnt(0)
	s_waitcnt lgkmcnt(0)
	v_mfma_f32_16x16x32_bf16 v[68:71], v[140:143], v[156:159], v[68:71]
	v_mfma_f32_16x16x32_bf16 v[64:67], v[148:151], v[156:159], v[64:67]
	v_mfma_f32_16x16x32_bf16 v[52:55], v[140:143], v[180:183], v[52:55]
	v_mfma_f32_16x16x32_bf16 v[48:51], v[148:151], v[180:183], v[48:51]
	v_mfma_f32_16x16x32_bf16 v[36:39], v[140:143], v[188:191], v[36:39]
	v_mfma_f32_16x16x32_bf16 v[32:35], v[148:151], v[188:191], v[32:35]
	v_mfma_f32_16x16x32_bf16 v[20:23], v[140:143], v[222:225], v[20:23]
	v_mfma_f32_16x16x32_bf16 v[16:19], v[148:151], v[222:225], v[16:19]
	v_mfma_f32_16x16x32_bf16 v[68:71], v[144:147], v[160:163], v[68:71]
	v_mfma_f32_16x16x32_bf16 v[64:67], v[152:155], v[160:163], v[64:67]
	v_mfma_f32_16x16x32_bf16 v[52:55], v[144:147], v[184:187], v[52:55]
	v_mfma_f32_16x16x32_bf16 v[48:51], v[152:155], v[184:187], v[48:51]
	v_mfma_f32_16x16x32_bf16 v[36:39], v[144:147], v[192:195], v[36:39]
	v_mfma_f32_16x16x32_bf16 v[32:35], v[152:155], v[192:195], v[32:35]
	v_mfma_f32_16x16x32_bf16 v[20:23], v[144:147], v[226:229], v[20:23]
	v_mfma_f32_16x16x32_bf16 v[16:19], v[152:155], v[226:229], v[16:19]
	s_barrier
	s_add_i32 m0, s65, 0x1c000
	s_add_u32 s56, s60, 0x100080
	s_addc_u32 s57, s61, 0
	global_load_lds_dwordx4 v0, s[56:57]
	s_add_i32 m0, s65, 0x1e000
	s_add_i32 s79, s79, 2
	global_load_lds_dwordx4 v2, s[56:57]
	s_add_u32 s77, s77, 0x100
	s_addc_u32 s78, s78, 0
	s_mov_b64 s[56:57], s[58:59]
	s_cmp_gt_u32 s79, 61
	s_cbranch_scc1 .LrotX_744
	ds_read_b128 v[140:143], v217
	ds_read_b128 v[144:147], v217 offset:1024
	ds_read_b128 v[148:151], v217 offset:2048
	ds_read_b128 v[152:155], v217 offset:3072
	s_cmp_lg_u32 s79, 60
	s_cselect_b64 s[60:61], -1, 0
	s_add_u32 s58, s56, 0x100
	s_addc_u32 s59, s57, 0
	s_and_b64 s[60:61], s[60:61], exec
	s_cselect_b32 s63, s59, s47
	s_cselect_b32 s62, s58, s46
	s_cselect_b32 s61, s78, s15
	s_cselect_b32 s60, s77, s49
; #define G_STAGE(bufoff, gbase) do { _Pragma("unroll") for (int _i = 0; _i < 2; ++_i) \
;         __builtin_amdgcn_global_load_lds((const unsigned*)((const char*)(gbase) + voff[_i]), (LAS unsigned*)(lds + (bufoff) + ldsw + _i * 8192), 16, 0, 0); } while (0)
; #define G_MMA(ai, bj, At, Bt) do { __builtin_amdgcn_s_setprio(1); _Pragma("unroll") for (int m = 0; m < 4; ++m) _Pragma("unroll") for (int n = 0; n < 2; ++n) _Pragma("unroll") for (int k = 0; k < 2; ++k) \
;         acc[ai][bj][m][n] = MFMA16(Bt[n][k], At[m][k], acc[ai][bj][m][n]); __builtin_amdgcn_s_setprio(0); } while (0)
; #define G_WAIT_V(n) asm volatile("s_waitcnt vmcnt(" #n ")" ::: "memory")
; #define G_BAR __builtin_amdgcn_s_barrier()
; template <class Epi>
; __device__ __forceinline__ void gemm_phase(LAS unsigned char* lds, const bf16_t* Ag, const bf16_t* Btg, const int K, const int nM, const int nN, const Epi& E) {
;     ...
;             G_STAGE(G_SB(1, 1), b3 + hstep);
;             G_WAIT_V(6); G_BAR; G_MMA(1, 1, At, B1); G_BAR;
;         }
.LrotX_744:
	s_waitcnt vmcnt(6)
	s_barrier
	v_mfma_f32_16x16x32_bf16 v[60:63], v[230:233], v[156:159], v[60:63]
	v_mfma_f32_16x16x32_bf16 v[56:59], v[238:241], v[156:159], v[56:59]
	v_mfma_f32_16x16x32_bf16 v[44:47], v[230:233], v[180:183], v[44:47]
	v_mfma_f32_16x16x32_bf16 v[40:43], v[238:241], v[180:183], v[40:43]
	v_mfma_f32_16x16x32_bf16 v[28:31], v[230:233], v[188:191], v[28:31]
	v_mfma_f32_16x16x32_bf16 v[24:27], v[238:241], v[188:191], v[24:27]
	v_mfma_f32_16x16x32_bf16 v[12:15], v[230:233], v[222:225], v[12:15]
	v_mfma_f32_16x16x32_bf16 v[8:11], v[238:241], v[222:225], v[8:11]
	v_mfma_f32_16x16x32_bf16 v[60:63], v[234:237], v[160:163], v[60:63]
	v_mfma_f32_16x16x32_bf16 v[56:59], v[242:245], v[160:163], v[56:59]
	v_mfma_f32_16x16x32_bf16 v[44:47], v[234:237], v[184:187], v[44:47]
	v_mfma_f32_16x16x32_bf16 v[40:43], v[242:245], v[184:187], v[40:43]
	v_mfma_f32_16x16x32_bf16 v[28:31], v[234:237], v[192:195], v[28:31]
	v_mfma_f32_16x16x32_bf16 v[24:27], v[242:245], v[192:195], v[24:27]
	v_mfma_f32_16x16x32_bf16 v[12:15], v[234:237], v[226:229], v[12:15]
	v_mfma_f32_16x16x32_bf16 v[8:11], v[242:245], v[226:229], v[8:11]
	s_cmp_gt_u32 s79, 61
	s_barrier
	s_cbranch_scc1 .LBB0_748
	s_cmp_lg_u32 s79, 60
	s_cbranch_scc1 .LmainW_744
	s_waitcnt lgkmcnt(0)

;     __device__ __forceinline__ void prep(int pm, int par, LAS unsigned char* lds) const { if (fold) prep_rowstats(stat, pm, par, lds); }
;     __device__ __forceinline__ void prep(int pm, int par, LAS unsigned char* lds) const { if (!ident) prep_rowstats(stat, pm, par, lds); }
;     __device__ __forceinline__ void prep(int pm, int par, LAS unsigned char* lds) const { prep_rowstats(stat, pm, par, lds); }
; #define G_STAGE(bufoff, gbase) do { _Pragma("unroll") for (int _i = 0; _i < 2; ++_i) \
;         __builtin_amdgcn_global_load_lds((const unsigned*)((const char*)(gbase) + voff[_i]), (LAS unsigned*)(lds + (bufoff) + ldsw + _i * 8192), 16, 0, 0); } while (0)
; #define G_LDA(dst, b, h) do { _Pragma("unroll") for (int m = 0; m < 4; ++m) _Pragma("unroll") for (int k = 0; k < 2; ++k) dst[m][k] = *(const LAS bf16x8*)(lds + G_SA(b, h) + aoff + m * 2048 + k * 1024); } while (0)
; #define G_LDB(dst, b, h) do { _Pragma("unroll") for (int n = 0; n < 2; ++n) _Pragma("unroll") for (int k = 0; k < 2; ++k) dst[n][k] = *(const LAS bf16x8*)(lds + G_SB(b, h) + boff + n * 2048 + k * 1024); } while (0)
; #define G_WAIT_V(n) asm volatile("s_waitcnt vmcnt(" #n ")" ::: "memory")
; #define G_WAIT_L(n) asm volatile("s_waitcnt lgkmcnt(" #n ")" ::: "memory")
; #define G_BAR __builtin_amdgcn_s_barrier()
; template <class Epi>
; __device__ __forceinline__ void gemm_phase(LAS unsigned char* lds, const bf16_t* Ag, const bf16_t* Btg, const int K, const int nM, const int nN, const Epi& E) {
;     ...
;             const char* a1 = cA + (size_t)(t + 1) * kstep;
;             const char* a2 = last ? nA : cA + (size_t)(t + 2) * kstep; const char* b2 = last ? nB : cB + (size_t)(t + 2) * kstep;
;             const char* a3 = a2 + kstep; const char* b3 = b2 + kstep;
;             if (last && has_next && pmn != pm) E.prep(pmn, par ^ 1, lds);
;             G_LDB(B0, 0, 0); G_SCHED; G_LDA(At, 0, 0); G_STAGE(G_SA(1, 1), a1 + hstep);
;             G_WAIT_L(8); G_BAR; G_WAIT_L(0); G_MMA(0, 0, At, B0); G_BAR; G_SCHED;
;             G_LDB(B1, 0, 1); G_STAGE(G_SB(0, 0), b2);
;             G_BAR; G_WAIT_L(0); G_MMA(0, 1, At, B1); G_BAR;
;             G_LDA(At, 0, 1); G_STAGE(G_SA(0, 0), a2);
;             G_BAR; G_WAIT_L(0); G_MMA(1, 0, At, B0); G_BAR; G_SCHED;
;             G_STAGE(G_SB(0, 1), b2 + hstep);
;             G_WAIT_V(6); G_BAR; G_MMA(1, 1, At, B1); G_BAR;
.LBB0_848:
	s_add_u32 s26, s50, 0xfffc0080
	s_addc_u32 s54, s51, -1
	s_and_b64 s[52:53], s[52:53], exec
	s_cselect_b32 s55, s54, s25
	s_cselect_b32 s54, s26, s24
	s_cselect_b32 s53, s71, s14
	s_cselect_b32 s52, s70, s15
	ds_read_b128 v[130:133], v217
	ds_read_b128 v[134:137], v217 offset:1024
	ds_read_b128 v[144:147], v217 offset:2048
	ds_read_b128 v[148:151], v217 offset:3072
.LmainW_848:
	s_add_i32 m0, s60, 0xc000
	ds_read_b128 v[156:159], v222
	ds_read_b128 v[160:163], v222 offset:1024
	ds_read_b128 v[164:167], v222 offset:2048
	ds_read_b128 v[180:183], v222 offset:3072
	ds_read_b128 v[184:187], v222 offset:4096
	ds_read_b128 v[224:227], v222 offset:5120
	ds_read_b128 v[228:231], v222 offset:6144
	global_load_lds_dwordx4 v170, s[50:51]
	s_add_i32 m0, s60, 0xe000
	ds_read_b128 v[232:235], v222 offset:7168
	global_load_lds_dwordx4 v168, s[50:51]
	s_waitcnt lgkmcnt(8)
	s_barrier
	s_waitcnt lgkmcnt(0)
	s_waitcnt lgkmcnt(0)
	v_mfma_f32_16x16x32_bf16 v[152:155], v[130:133], v[156:159], v[152:155]
	v_mfma_f32_16x16x32_bf16 v[138:141], v[144:147], v[156:159], v[140:143]
	v_mfma_f32_16x16x32_bf16 v[116:119], v[130:133], v[164:167], v[116:119]
	v_mfma_f32_16x16x32_bf16 v[112:115], v[144:147], v[164:167], v[112:115]
	v_mfma_f32_16x16x32_bf16 v[100:103], v[130:133], v[184:187], v[100:103]
	v_mfma_f32_16x16x32_bf16 v[96:99], v[144:147], v[184:187], v[96:99]
	v_mfma_f32_16x16x32_bf16 v[84:87], v[130:133], v[228:231], v[84:87]
	v_mfma_f32_16x16x32_bf16 v[80:83], v[144:147], v[228:231], v[80:83]
	v_mfma_f32_16x16x32_bf16 v[152:155], v[134:137], v[160:163], v[152:155]
	v_mfma_f32_16x16x32_bf16 v[138:141], v[148:151], v[160:163], v[138:141]
	v_mfma_f32_16x16x32_bf16 v[116:119], v[134:137], v[180:183], v[116:119]
	v_mfma_f32_16x16x32_bf16 v[112:115], v[148:151], v[180:183], v[112:115]
	v_mfma_f32_16x16x32_bf16 v[100:103], v[134:137], v[224:227], v[100:103]
	v_mfma_f32_16x16x32_bf16 v[96:99], v[148:151], v[224:227], v[96:99]
	v_mfma_f32_16x16x32_bf16 v[84:87], v[134:137], v[232:235], v[84:87]
	v_mfma_f32_16x16x32_bf16 v[80:83], v[148:151], v[232:235], v[80:83]
	s_barrier
	s_add_i32 s73, 0, 0x14000
	s_add_i32 m0, s59, 0x10000
	ds_read_b128 v[236:239], v217 offset:16384
	ds_read_b128 v[240:243], v217 offset:17408
	ds_read_b128 v[244:247], v217 offset:18432
	global_load_lds_dwordx4 v0, s[52:53]
	s_add_i32 m0, s59, 0x12000
	ds_read_b128 v[248:251], v217 offset:19456
	global_load_lds_dwordx4 v2, s[52:53]
	s_barrier
	s_waitcnt lgkmcnt(0)
	s_waitcnt lgkmcnt(0)
	v_mfma_f32_16x16x32_bf16 v[124:127], v[236:239], v[156:159], v[124:127]
	v_mfma_f32_16x16x32_bf16 v[120:123], v[244:247], v[156:159], v[120:123]
	v_mfma_f32_16x16x32_bf16 v[108:111], v[236:239], v[164:167], v[108:111]
	v_mfma_f32_16x16x32_bf16 v[104:107], v[244:247], v[164:167], v[104:107]
	v_mfma_f32_16x16x32_bf16 v[92:95], v[236:239], v[184:187], v[92:95]
	v_mfma_f32_16x16x32_bf16 v[88:91], v[244:247], v[184:187], v[88:91]
	v_mfma_f32_16x16x32_bf16 v[76:79], v[236:239], v[228:231], v[76:79]
	v_mfma_f32_16x16x32_bf16 v[72:75], v[244:247], v[228:231], v[72:75]
	v_mfma_f32_16x16x32_bf16 v[124:127], v[240:243], v[160:163], v[124:127]
	v_mfma_f32_16x16x32_bf16 v[120:123], v[248:251], v[160:163], v[120:123]
	v_mfma_f32_16x16x32_bf16 v[108:111], v[240:243], v[180:183], v[108:111]
	v_mfma_f32_16x16x32_bf16 v[104:107], v[248:251], v[180:183], v[104:107]
	v_mfma_f32_16x16x32_bf16 v[92:95], v[240:243], v[224:227], v[92:95]
	v_mfma_f32_16x16x32_bf16 v[88:91], v[248:251], v[224:227], v[88:91]
	v_mfma_f32_16x16x32_bf16 v[76:79], v[240:243], v[232:235], v[76:79]
	v_mfma_f32_16x16x32_bf16 v[72:75], v[248:251], v[232:235], v[72:75]
	s_mov_b32 m0, s60
	s_add_u32 s76, s54, 0x80
	s_addc_u32 s77, s55, 0
	s_barrier
	ds_read_b128 v[156:159], v222 offset:16384
	ds_read_b128 v[160:163], v222 offset:17408
	ds_read_b128 v[164:167], v222 offset:18432
	ds_read_b128 v[180:183], v222 offset:19456
	ds_read_b128 v[184:187], v222 offset:20480
	ds_read_b128 v[224:227], v222 offset:21504
	ds_read_b128 v[228:231], v222 offset:22528
	ds_read_b128 v[232:235], v222 offset:23552
	global_load_lds_dwordx4 v0, s[54:55]
	s_add_u32 s76, s54, 0x80
	s_mov_b32 m0, s61
	s_addc_u32 s77, s55, 0
	global_load_lds_dwordx4 v2, s[54:55]
	s_waitcnt vmcnt(10)
	s_barrier
	s_waitcnt lgkmcnt(0)
	s_waitcnt lgkmcnt(0)
	v_mfma_f32_16x16x32_bf16 v[60:63], v[130:133], v[156:159], v[60:63]
	v_mfma_f32_16x16x32_bf16 v[56:59], v[144:147], v[156:159], v[56:59]
	v_mfma_f32_16x16x32_bf16 v[44:47], v[130:133], v[164:167], v[44:47]
	v_mfma_f32_16x16x32_bf16 v[40:43], v[144:147], v[164:167], v[40:43]
	v_mfma_f32_16x16x32_bf16 v[28:31], v[130:133], v[184:187], v[28:31]
	v_mfma_f32_16x16x32_bf16 v[24:27], v[144:147], v[184:187], v[24:27]
	v_mfma_f32_16x16x32_bf16 v[12:15], v[130:133], v[228:231], v[12:15]
	v_mfma_f32_16x16x32_bf16 v[8:11], v[144:147], v[228:231], v[8:11]
	v_mfma_f32_16x16x32_bf16 v[60:63], v[134:137], v[160:163], v[60:63]
	v_mfma_f32_16x16x32_bf16 v[56:59], v[148:151], v[160:163], v[56:59]
	v_mfma_f32_16x16x32_bf16 v[44:47], v[134:137], v[180:183], v[44:47]
	v_mfma_f32_16x16x32_bf16 v[40:43], v[148:151], v[180:183], v[40:43]
	v_mfma_f32_16x16x32_bf16 v[28:31], v[134:137], v[224:227], v[28:31]
	v_mfma_f32_16x16x32_bf16 v[24:27], v[148:151], v[224:227], v[24:27]
	v_mfma_f32_16x16x32_bf16 v[12:15], v[134:137], v[232:235], v[12:15]
	v_mfma_f32_16x16x32_bf16 v[8:11], v[148:151], v[232:235], v[8:11]
	s_barrier
	ds_read_b128 v[130:133], v217 offset:32768
	ds_read_b128 v[134:137], v217 offset:33792
	ds_read_b128 v[144:147], v217 offset:34816
	ds_read_b128 v[148:151], v217 offset:35840
	s_add_i32 m0, s59, 0x14000
	s_add_u32 s74, s52, 0x40000
	s_addc_u32 s75, s53, 0
	global_load_lds_dwordx4 v0, s[74:75]
	s_add_i32 m0, s59, 0x16000
	s_add_u32 s54, s54, 0x40000
	s_addc_u32 s55, s55, 0
	global_load_lds_dwordx4 v2, s[74:75]
	s_waitcnt vmcnt(6)
	s_barrier
; #define G_STAGE(bufoff, gbase) do { _Pragma("unroll") for (int _i = 0; _i < 2; ++_i) \
;         __builtin_amdgcn_global_load_lds((const unsigned*)((const char*)(gbase) + voff[_i]), (LAS unsigned*)(lds + (bufoff) + ldsw + _i * 8192), 16, 0, 0); } while (0)
; #define G_LDA(dst, b, h) do { _Pragma("unroll") for (int m = 0; m < 4; ++m) _Pragma("unroll") for (int k = 0; k < 2; ++k) dst[m][k] = *(const LAS bf16x8*)(lds + G_SA(b, h) + aoff + m * 2048 + k * 1024); } while (0)
; #define G_LDB(dst, b, h) do { _Pragma("unroll") for (int n = 0; n < 2; ++n) _Pragma("unroll") for (int k = 0; k < 2; ++k) dst[n][k] = *(const LAS bf16x8*)(lds + G_SB(b, h) + boff + n * 2048 + k * 1024); } while (0)
; #define G_MMA(ai, bj, At, Bt) do { __builtin_amdgcn_s_setprio(1); _Pragma("unroll") for (int m = 0; m < 4; ++m) _Pragma("unroll") for (int n = 0; n < 2; ++n) _Pragma("unroll") for (int k = 0; k < 2; ++k) \
;         acc[ai][bj][m][n] = MFMA16(Bt[n][k], At[m][k], acc[ai][bj][m][n]); __builtin_amdgcn_s_setprio(0); } while (0)
; #define G_WAIT_V(n) asm volatile("s_waitcnt vmcnt(" #n ")" ::: "memory")
; #define G_WAIT_L(n) asm volatile("s_waitcnt lgkmcnt(" #n ")" ::: "memory")
; #define G_BAR __builtin_amdgcn_s_barrier()
; #define G_SCHED __builtin_amdgcn_sched_barrier(0)
; template <class Epi>
; __device__ __forceinline__ void gemm_phase(LAS unsigned char* lds, const bf16_t* Ag, const bf16_t* Btg, const int K, const int nM, const int nN, const Epi& E) {
;     ...
;             const char* a1 = cA + (size_t)(t + 1) * kstep;
;             const char* a2 = last ? nA : cA + (size_t)(t + 2) * kstep; const char* b2 = last ? nB : cB + (size_t)(t + 2) * kstep;
;             const char* a3 = a2 + kstep; const char* b3 = b2 + kstep;
;     ...
;             G_WAIT_V(6); G_BAR; G_MMA(1, 1, At, B1); G_BAR;
;             G_LDB(B0, 1, 0); G_SCHED; G_LDA(At, 1, 0); G_STAGE(G_SA(0, 1), a2 + hstep);
;             G_WAIT_L(8); G_BAR; G_WAIT_L(0); G_MMA(0, 0, At, B0); G_BAR; G_SCHED;
;             G_LDB(B1, 1, 1); G_STAGE(G_SB(1, 0), b3);
;             G_BAR; G_WAIT_L(0); G_MMA(0, 1, At, B1); G_BAR;
;             G_LDA(At, 1, 1); G_STAGE(G_SA(1, 0), a3);
;             G_BAR; G_WAIT_L(0); G_MMA(1, 0, At, B0); G_BAR; G_SCHED;
;             G_STAGE(G_SB(1, 1), b3 + hstep);
;             G_WAIT_V(6); G_BAR; G_MMA(1, 1, At, B1); G_BAR;
	v_mfma_f32_16x16x32_bf16 v[68:71], v[236:239], v[156:159], v[68:71]
	v_mfma_f32_16x16x32_bf16 v[64:67], v[244:247], v[156:159], v[64:67]
	v_mfma_f32_16x16x32_bf16 v[52:55], v[236:239], v[164:167], v[52:55]
	v_mfma_f32_16x16x32_bf16 v[48:51], v[244:247], v[164:167], v[48:51]
	v_mfma_f32_16x16x32_bf16 v[36:39], v[236:239], v[184:187], v[36:39]
	v_mfma_f32_16x16x32_bf16 v[32:35], v[244:247], v[184:187], v[32:35]
	v_mfma_f32_16x16x32_bf16 v[20:23], v[236:239], v[228:231], v[20:23]
	v_mfma_f32_16x16x32_bf16 v[16:19], v[244:247], v[228:231], v[16:19]
	v_mfma_f32_16x16x32_bf16 v[68:71], v[240:243], v[160:163], v[68:71]
	v_mfma_f32_16x16x32_bf16 v[64:67], v[248:251], v[160:163], v[64:67]
	v_mfma_f32_16x16x32_bf16 v[52:55], v[240:243], v[180:183], v[52:55]
	v_mfma_f32_16x16x32_bf16 v[48:51], v[248:251], v[180:183], v[48:51]
	v_mfma_f32_16x16x32_bf16 v[36:39], v[240:243], v[224:227], v[36:39]
	v_mfma_f32_16x16x32_bf16 v[32:35], v[248:251], v[224:227], v[32:35]
	v_mfma_f32_16x16x32_bf16 v[20:23], v[240:243], v[232:235], v[20:23]
	v_mfma_f32_16x16x32_bf16 v[16:19], v[248:251], v[232:235], v[16:19]
	s_barrier
	s_mov_b32 m0, s62
	ds_read_b128 v[156:159], v222 offset:32768
	ds_read_b128 v[160:163], v222 offset:33792
	ds_read_b128 v[164:167], v222 offset:34816
	ds_read_b128 v[180:183], v222 offset:35840
	ds_read_b128 v[184:187], v222 offset:36864
	ds_read_b128 v[224:227], v222 offset:37888
	ds_read_b128 v[228:231], v222 offset:38912
	global_load_lds_dwordx4 v0, s[54:55]
	s_mov_b32 m0, s63
	ds_read_b128 v[232:235], v222 offset:39936
	global_load_lds_dwordx4 v2, s[54:55]
	s_waitcnt lgkmcnt(8)
	s_barrier
	s_waitcnt lgkmcnt(0)
	s_waitcnt lgkmcnt(0)
	v_mfma_f32_16x16x32_bf16 v[152:155], v[130:133], v[156:159], v[152:155]
	v_mfma_f32_16x16x32_bf16 v[138:141], v[144:147], v[156:159], v[138:141]
	v_mfma_f32_16x16x32_bf16 v[116:119], v[130:133], v[164:167], v[116:119]
	v_mfma_f32_16x16x32_bf16 v[112:115], v[144:147], v[164:167], v[112:115]
	v_mfma_f32_16x16x32_bf16 v[100:103], v[130:133], v[184:187], v[100:103]
	v_mfma_f32_16x16x32_bf16 v[96:99], v[144:147], v[184:187], v[96:99]
	v_mfma_f32_16x16x32_bf16 v[84:87], v[130:133], v[228:231], v[84:87]
	v_mfma_f32_16x16x32_bf16 v[80:83], v[144:147], v[228:231], v[80:83]
	v_mfma_f32_16x16x32_bf16 v[152:155], v[134:137], v[160:163], v[152:155]
	v_mfma_f32_16x16x32_bf16 v[140:143], v[148:151], v[160:163], v[138:141]
	v_mfma_f32_16x16x32_bf16 v[116:119], v[134:137], v[180:183], v[116:119]
	v_mfma_f32_16x16x32_bf16 v[112:115], v[148:151], v[180:183], v[112:115]
	v_mfma_f32_16x16x32_bf16 v[100:103], v[134:137], v[224:227], v[100:103]
	v_mfma_f32_16x16x32_bf16 v[96:99], v[148:151], v[224:227], v[96:99]
	v_mfma_f32_16x16x32_bf16 v[84:87], v[134:137], v[232:235], v[84:87]
	v_mfma_f32_16x16x32_bf16 v[80:83], v[148:151], v[232:235], v[80:83]
	s_barrier
	s_add_i32 m0, s59, 0x18000
	ds_read_b128 v[236:239], v217 offset:49152
	ds_read_b128 v[240:243], v217 offset:50176
	ds_read_b128 v[244:247], v217 offset:51200
	s_add_u32 s98, s52, 0x80
	s_addc_u32 s99, s53, 0
	global_load_lds_dwordx4 v0, s[98:99]
	s_add_i32 m0, s59, 0x1a000
	ds_read_b128 v[248:251], v217 offset:52224
	global_load_lds_dwordx4 v2, s[98:99]
	s_barrier
	s_waitcnt lgkmcnt(0)
	s_waitcnt lgkmcnt(0)
	v_mfma_f32_16x16x32_bf16 v[124:127], v[236:239], v[156:159], v[124:127]
	v_mfma_f32_16x16x32_bf16 v[120:123], v[244:247], v[156:159], v[120:123]
	v_mfma_f32_16x16x32_bf16 v[108:111], v[236:239], v[164:167], v[108:111]
	v_mfma_f32_16x16x32_bf16 v[104:107], v[244:247], v[164:167], v[104:107]
	v_mfma_f32_16x16x32_bf16 v[92:95], v[236:239], v[184:187], v[92:95]
	v_mfma_f32_16x16x32_bf16 v[88:91], v[244:247], v[184:187], v[88:91]
	v_mfma_f32_16x16x32_bf16 v[76:79], v[236:239], v[228:231], v[76:79]
	v_mfma_f32_16x16x32_bf16 v[72:75], v[244:247], v[228:231], v[72:75]
	v_mfma_f32_16x16x32_bf16 v[124:127], v[240:243], v[160:163], v[124:127]
	v_mfma_f32_16x16x32_bf16 v[120:123], v[248:251], v[160:163], v[120:123]
	v_mfma_f32_16x16x32_bf16 v[108:111], v[240:243], v[180:183], v[108:111]
	v_mfma_f32_16x16x32_bf16 v[104:107], v[248:251], v[180:183], v[104:107]
	v_mfma_f32_16x16x32_bf16 v[92:95], v[240:243], v[224:227], v[92:95]
	v_mfma_f32_16x16x32_bf16 v[88:91], v[248:251], v[224:227], v[88:91]
	v_mfma_f32_16x16x32_bf16 v[76:79], v[240:243], v[232:235], v[76:79]
	v_mfma_f32_16x16x32_bf16 v[72:75], v[248:251], v[232:235], v[72:75]
	s_mov_b32 m0, s64
	s_barrier
	ds_read_b128 v[156:159], v222 offset:49152
	ds_read_b128 v[160:163], v222 offset:50176
	ds_read_b128 v[164:167], v222 offset:51200
	ds_read_b128 v[180:183], v222 offset:52224
	ds_read_b128 v[184:187], v222 offset:53248
	ds_read_b128 v[224:227], v222 offset:54272
	ds_read_b128 v[228:231], v222 offset:55296
	global_load_lds_dwordx4 v0, s[76:77]
	s_mov_b32 m0, s65
	ds_read_b128 v[232:235], v222 offset:56320
	global_load_lds_dwordx4 v2, s[76:77]
	s_waitcnt vmcnt(10)
	s_barrier
	s_waitcnt lgkmcnt(0)
	s_waitcnt lgkmcnt(0)
	v_mfma_f32_16x16x32_bf16 v[60:63], v[130:133], v[156:159], v[60:63]
	v_mfma_f32_16x16x32_bf16 v[56:59], v[144:147], v[156:159], v[56:59]
	v_mfma_f32_16x16x32_bf16 v[44:47], v[130:133], v[164:167], v[44:47]
	v_mfma_f32_16x16x32_bf16 v[40:43], v[144:147], v[164:167], v[40:43]
	v_mfma_f32_16x16x32_bf16 v[28:31], v[130:133], v[184:187], v[28:31]
	v_mfma_f32_16x16x32_bf16 v[24:27], v[144:147], v[184:187], v[24:27]
	v_mfma_f32_16x16x32_bf16 v[12:15], v[130:133], v[228:231], v[12:15]
	v_mfma_f32_16x16x32_bf16 v[8:11], v[144:147], v[228:231], v[8:11]
	v_mfma_f32_16x16x32_bf16 v[60:63], v[134:137], v[160:163], v[60:63]
	v_mfma_f32_16x16x32_bf16 v[56:59], v[148:151], v[160:163], v[56:59]
	v_mfma_f32_16x16x32_bf16 v[44:47], v[134:137], v[180:183], v[44:47]
	v_mfma_f32_16x16x32_bf16 v[40:43], v[148:151], v[180:183], v[40:43]
	v_mfma_f32_16x16x32_bf16 v[28:31], v[134:137], v[224:227], v[28:31]
	v_mfma_f32_16x16x32_bf16 v[24:27], v[148:151], v[224:227], v[24:27]
	v_mfma_f32_16x16x32_bf16 v[12:15], v[134:137], v[232:235], v[12:15]
	v_mfma_f32_16x16x32_bf16 v[8:11], v[148:151], v[232:235], v[8:11]
	s_barrier
	s_add_i32 m0, s59, 0x1c000
	s_add_u32 s52, s52, 0x40080
	s_addc_u32 s53, s53, 0
	global_load_lds_dwordx4 v0, s[52:53]
	s_add_i32 m0, s59, 0x1e000
	s_add_i32 s72, s72, 2
	global_load_lds_dwordx4 v2, s[52:53]
	s_add_u32 s70, s70, 0x100
	s_addc_u32 s71, s71, 0
	s_add_u32 s50, s50, 0x100
	s_addc_u32 s51, s51, 0
	s_cmp_gt_u32 s72, 13
	s_cbranch_scc1 .LrotX_848
	ds_read_b128 v[130:133], v217
	ds_read_b128 v[134:137], v217 offset:1024
	ds_read_b128 v[144:147], v217 offset:2048
	ds_read_b128 v[148:151], v217 offset:3072
	s_cmp_lg_u32 s72, 12
	s_cselect_b64 s[52:53], -1, 0
	s_add_u32 s26, s50, 0xfffc0080
	s_addc_u32 s54, s51, -1
	s_and_b64 s[52:53], s[52:53], exec
	s_cselect_b32 s55, s54, s25
	s_cselect_b32 s54, s26, s24
	s_cselect_b32 s53, s71, s14
	s_cselect_b32 s52, s70, s15
; #define G_STAGE(bufoff, gbase) do { _Pragma("unroll") for (int _i = 0; _i < 2; ++_i) \
;         __builtin_amdgcn_global_load_lds((const unsigned*)((const char*)(gbase) + voff[_i]), (LAS unsigned*)(lds + (bufoff) + ldsw + _i * 8192), 16, 0, 0); } while (0)
; #define G_MMA(ai, bj, At, Bt) do { __builtin_amdgcn_s_setprio(1); _Pragma("unroll") for (int m = 0; m < 4; ++m) _Pragma("unroll") for (int n = 0; n < 2; ++n) _Pragma("unroll") for (int k = 0; k < 2; ++k) \
;         acc[ai][bj][m][n] = MFMA16(Bt[n][k], At[m][k], acc[ai][bj][m][n]); __builtin_amdgcn_s_setprio(0); } while (0)
; #define G_WAIT_V(n) asm volatile("s_waitcnt vmcnt(" #n ")" ::: "memory")
; #define G_BAR __builtin_amdgcn_s_barrier()
; template <class Epi>
; __device__ __forceinline__ void gemm_phase(LAS unsigned char* lds, const bf16_t* Ag, const bf16_t* Btg, const int K, const int nM, const int nN, const Epi& E) {
;     ...
;             G_STAGE(G_SB(1, 1), b3 + hstep);
;             G_WAIT_V(6); G_BAR; G_MMA(1, 1, At, B1); G_BAR;
;         }
.LrotX_848:
	s_waitcnt vmcnt(6)
	s_barrier
	v_mfma_f32_16x16x32_bf16 v[68:71], v[236:239], v[156:159], v[68:71]
	v_mfma_f32_16x16x32_bf16 v[64:67], v[244:247], v[156:159], v[64:67]
	v_mfma_f32_16x16x32_bf16 v[52:55], v[236:239], v[164:167], v[52:55]
	v_mfma_f32_16x16x32_bf16 v[48:51], v[244:247], v[164:167], v[48:51]
	v_mfma_f32_16x16x32_bf16 v[36:39], v[236:239], v[184:187], v[36:39]
	v_mfma_f32_16x16x32_bf16 v[32:35], v[244:247], v[184:187], v[32:35]
	v_mfma_f32_16x16x32_bf16 v[20:23], v[236:239], v[228:231], v[20:23]
	v_mfma_f32_16x16x32_bf16 v[16:19], v[244:247], v[228:231], v[16:19]
	v_mfma_f32_16x16x32_bf16 v[68:71], v[240:243], v[160:163], v[68:71]
	v_mfma_f32_16x16x32_bf16 v[64:67], v[248:251], v[160:163], v[64:67]
	v_mfma_f32_16x16x32_bf16 v[52:55], v[240:243], v[180:183], v[52:55]
	v_mfma_f32_16x16x32_bf16 v[48:51], v[248:251], v[180:183], v[48:51]
	v_mfma_f32_16x16x32_bf16 v[36:39], v[240:243], v[224:227], v[36:39]
	v_mfma_f32_16x16x32_bf16 v[32:35], v[248:251], v[224:227], v[32:35]
	v_mfma_f32_16x16x32_bf16 v[20:23], v[240:243], v[232:235], v[20:23]
	v_mfma_f32_16x16x32_bf16 v[16:19], v[248:251], v[232:235], v[16:19]
	s_cmp_gt_u32 s72, 13
	s_barrier
	s_cbranch_scc1 .LBB0_852
	s_cmp_lg_u32 s72, 12
	s_cbranch_scc1 .LmainW_848
	s_waitcnt lgkmcnt(0)
